# retention output epilogue rewritten (gates via dwordx4+LDS, batched rms/silu, LDS transpose + dwordx4 stores) + attention epilogue + SwiGLU packed
# baseline (speedup 1.0000x reference)
; __device__ __forceinline__ int crow(int r, int hi) { return (r & 3) + 8 * (r >> 2) + 4 * hi; }
; __device__ __forceinline__ void ret_output_unit(const bf16* __restrict__ Rb, const bf16* __restrict__ Sf, const bf16* __restrict__ Sb, bf16* Y, long rowbase, int h, float lgf, float lgb, char* lds) {
;     ...
;     *(bf16x8*)((char*)V_lds + vst0) = v0; *(bf16x8*)((char*)V_lds + vst1) = v1;
;     *(bf16x8*)((char*)K_lds + KSWZ(sr, sc * 2)) = k0; *(bf16x8*)((char*)K_lds + KSWZ(32 + sr, sc * 2)) = k1;
;     __syncthreads();
;     f32x16 p0, p1; qkt(p0, p1, K_lds, qr, r32, hi);
; #pragma unroll
;     for (int r = 0; r < 16; ++r) {
;       const int ja = tile * 64 + crow(r, hi), jb = ja + 32; const float da = (float)(a - ja), db_ = (float)(a - jb);
;       const float wa = (da >= 0.f ? __builtin_amdgcn_exp2f(lgf * da) : 0.f) + (da <= 0.f ? __builtin_amdgcn_exp2f(-lgb * da) : 0.f);
;       const float wb = (db_ >= 0.f ? __builtin_amdgcn_exp2f(lgf * db_) : 0.f) + (db_ <= 0.f ? __builtin_amdgcn_exp2f(-lgb * db_) : 0.f);
;       p0[r] *= wa * SCALE; p1[r] *= wb * SCALE; }
.LBB0_1007:
	ds_write_b128 v155, v[74:77]
	ds_write_b128 v156, v[78:81]
	ds_write_b128 v157, v[66:69] offset:16384
	ds_write_b128 v158, v[70:73] offset:16384
	s_waitcnt lgkmcnt(0)
	s_barrier
	ds_read_b128 v[66:69], v159 offset:16384
	ds_read_b128 v[82:85], v159 offset:24576
	s_waitcnt lgkmcnt(1)
	v_mfma_f32_32x32x16_bf16 v[66:81], v[66:69], v[98:101], 0
	ds_read_b128 v[168:171], v160 offset:16384
	ds_read_b128 v[172:175], v160 offset:24576
	v_add_u32_e32 v167, s11, v154
	v_cmp_lt_i32_e32 vcc, -1, v167
	s_waitcnt lgkmcnt(2)
	v_mfma_f32_32x32x16_bf16 v[82:97], v[82:85], v[98:101], 0
	s_waitcnt lgkmcnt(1)
	v_mfma_f32_32x32x16_bf16 v[66:81], v[168:171], v[102:105], v[66:81]
	s_waitcnt lgkmcnt(0)
	v_mfma_f32_32x32x16_bf16 v[82:97], v[172:175], v[102:105], v[82:97]
	ds_read_b128 v[168:171], v161 offset:16384
	ds_read_b128 v[172:175], v161 offset:24576
	s_waitcnt lgkmcnt(1)
	v_mfma_f32_32x32x16_bf16 v[66:81], v[168:171], v[106:109], v[66:81]
	s_waitcnt lgkmcnt(0)
	v_mfma_f32_32x32x16_bf16 v[82:97], v[172:175], v[106:109], v[82:97]
	ds_read_b128 v[168:171], v162 offset:16384
	ds_read_b128 v[172:175], v162 offset:24576
	s_waitcnt lgkmcnt(1)
	v_mfma_f32_32x32x16_bf16 v[66:81], v[168:171], v[110:113], v[66:81]
	s_waitcnt lgkmcnt(0)
	v_mfma_f32_32x32x16_bf16 v[82:97], v[172:175], v[110:113], v[82:97]
	ds_read_b128 v[168:171], v163 offset:16384
	ds_read_b128 v[172:175], v163 offset:24576
	s_waitcnt lgkmcnt(1)
	v_mfma_f32_32x32x16_bf16 v[66:81], v[168:171], v[114:117], v[66:81]
	s_waitcnt lgkmcnt(0)
	v_mfma_f32_32x32x16_bf16 v[82:97], v[172:175], v[114:117], v[82:97]
	ds_read_b128 v[168:171], v164 offset:16384
	ds_read_b128 v[172:175], v164 offset:24576
	s_waitcnt lgkmcnt(1)
	v_mfma_f32_32x32x16_bf16 v[66:81], v[168:171], v[118:121], v[66:81]
	s_waitcnt lgkmcnt(0)
	v_mfma_f32_32x32x16_bf16 v[82:97], v[172:175], v[118:121], v[82:97]
	ds_read_b128 v[168:171], v165 offset:16384
	ds_read_b128 v[172:175], v165 offset:24576
	s_waitcnt lgkmcnt(1)
	v_mfma_f32_32x32x16_bf16 v[66:81], v[168:171], v[122:125], v[66:81]
	s_waitcnt lgkmcnt(0)
	v_mfma_f32_32x32x16_bf16 v[82:97], v[172:175], v[122:125], v[82:97]
	ds_read_b128 v[168:171], v166 offset:16384
	ds_read_b128 v[172:175], v166 offset:24576
	s_waitcnt lgkmcnt(1)
	v_mfma_f32_32x32x16_bf16 v[66:81], v[168:171], v[126:129], v[66:81]
	v_cvt_f32_i32_e32 v168, v167
	v_subrev_u32_e32 v169, 32, v167
	v_cvt_f32_i32_e32 v170, v169
	v_mul_f32_e32 v171, v147, v168
	v_exp_f32_e32 v171, v171
	v_mul_f32_e64 v168, -v152, v168
	v_exp_f32_e32 v168, v168
	s_waitcnt lgkmcnt(0)
	v_mfma_f32_32x32x16_bf16 v[82:97], v[172:175], v[126:129], v[82:97]
	v_cndmask_b32_e32 v171, 0, v171, vcc
	v_cmp_gt_i32_e32 vcc, 1, v167
	s_nop 1
	v_cndmask_b32_e32 v168, 0, v168, vcc
	v_add_f32_e32 v168, v171, v168
	v_mul_f32_e32 v171, v147, v170
	v_exp_f32_e32 v171, v171
	v_cmp_lt_i32_e32 vcc, -1, v169
	v_mul_f32_e32 v168, 0x3db504f3, v168
	v_mul_f32_e32 v168, v168, v66
	v_cndmask_b32_e32 v171, 0, v171, vcc
	v_cmp_gt_i32_e32 vcc, 1, v169
	v_mul_f32_e64 v169, -v152, v170
	v_exp_f32_e32 v169, v169
	v_subrev_u32_e32 v170, 33, v167
	v_cndmask_b32_e32 v169, 0, v169, vcc
	v_add_f32_e32 v169, v171, v169
	v_mul_f32_e32 v66, 0x3db504f3, v169
	v_mul_f32_e32 v66, v66, v82
	v_add_u32_e32 v82, -1, v167
	v_cvt_f32_i32_e32 v169, v82
	v_cvt_f32_i32_e32 v171, v170
	v_cmp_lt_i32_e32 vcc, -1, v82
	v_mul_f32_e32 v172, v147, v169
	v_exp_f32_e32 v172, v172
	s_nop 0
	v_cndmask_b32_e32 v172, 0, v172, vcc
	v_cmp_gt_i32_e32 vcc, 1, v82
	v_mul_f32_e64 v82, -v152, v169
	v_exp_f32_e32 v82, v82
	v_mul_f32_e32 v169, v147, v171
	v_exp_f32_e32 v169, v169
	v_cndmask_b32_e32 v82, 0, v82, vcc
	v_cmp_lt_i32_e32 vcc, -1, v170
	v_add_f32_e32 v82, v172, v82
	v_mul_f32_e32 v82, 0x3db504f3, v82
	v_cndmask_b32_e32 v169, 0, v169, vcc
	v_cmp_gt_i32_e32 vcc, 1, v170
	v_mul_f32_e64 v170, -v152, v171
	v_exp_f32_e32 v170, v170
	v_mul_f32_e32 v82, v82, v67
	v_cndmask_b32_e32 v170, 0, v170, vcc
	v_add_f32_e32 v169, v169, v170
	v_mul_f32_e32 v67, 0x3db504f3, v169
	v_mul_f32_e32 v67, v67, v83
	v_add_u32_e32 v83, -2, v167
	v_cvt_f32_i32_e32 v169, v83
	v_subrev_u32_e32 v170, 34, v167
	v_cvt_f32_i32_e32 v171, v170
	v_cmp_lt_i32_e32 vcc, -1, v83
	v_mul_f32_e32 v172, v147, v169
	v_exp_f32_e32 v172, v172
	s_nop 0
	v_cndmask_b32_e32 v172, 0, v172, vcc
	v_cmp_gt_i32_e32 vcc, 1, v83
	v_mul_f32_e64 v83, -v152, v169
	v_exp_f32_e32 v83, v83
	v_mul_f32_e32 v169, v147, v171
	v_exp_f32_e32 v169, v169
	v_cndmask_b32_e32 v83, 0, v83, vcc
	v_cmp_lt_i32_e32 vcc, -1, v170
	v_add_f32_e32 v83, v172, v83
	v_mul_f32_e32 v83, 0x3db504f3, v83
	v_cndmask_b32_e32 v169, 0, v169, vcc
	v_cmp_gt_i32_e32 vcc, 1, v170
	v_mul_f32_e64 v170, -v152, v171
	v_exp_f32_e32 v170, v170
	v_mul_f32_e32 v83, v83, v68
	v_cndmask_b32_e32 v170, 0, v170, vcc
	v_add_f32_e32 v169, v169, v170
	v_mul_f32_e32 v68, 0x3db504f3, v169
	v_mul_f32_e32 v68, v68, v84
	v_add_u32_e32 v84, -3, v167
	v_cvt_f32_i32_e32 v169, v84
	v_subrev_u32_e32 v170, 35, v167
	v_cvt_f32_i32_e32 v171, v170
	v_cmp_lt_i32_e32 vcc, -1, v84
	v_mul_f32_e32 v172, v147, v169
	v_exp_f32_e32 v172, v172
	s_nop 0
	v_cndmask_b32_e32 v172, 0, v172, vcc
	v_cmp_gt_i32_e32 vcc, 1, v84
	v_mul_f32_e64 v84, -v152, v169
	v_exp_f32_e32 v84, v84
	v_mul_f32_e32 v169, v147, v171
	v_exp_f32_e32 v169, v169
	v_cndmask_b32_e32 v84, 0, v84, vcc
	v_cmp_lt_i32_e32 vcc, -1, v170
	v_add_f32_e32 v84, v172, v84
	v_mul_f32_e32 v84, 0x3db504f3, v84
	v_cndmask_b32_e32 v169, 0, v169, vcc
	v_cmp_gt_i32_e32 vcc, 1, v170
	v_mul_f32_e64 v170, -v152, v171
	v_exp_f32_e32 v170, v170
	v_mul_f32_e32 v84, v84, v69
	v_cndmask_b32_e32 v170, 0, v170, vcc
	v_add_f32_e32 v169, v169, v170
	v_mul_f32_e32 v69, 0x3db504f3, v169
; __device__ __forceinline__ int crow(int r, int hi) { return (r & 3) + 8 * (r >> 2) + 4 * hi; }
; __device__ __forceinline__ void ret_output_unit(const bf16* __restrict__ Rb, const bf16* __restrict__ Sf, const bf16* __restrict__ Sb, bf16* Y, long rowbase, int h, float lgf, float lgb, char* lds) {
;     ...
;     for (int r = 0; r < 16; ++r) {
;       const int ja = tile * 64 + crow(r, hi), jb = ja + 32; const float da = (float)(a - ja), db_ = (float)(a - jb);
;       const float wa = (da >= 0.f ? __builtin_amdgcn_exp2f(lgf * da) : 0.f) + (da <= 0.f ? __builtin_amdgcn_exp2f(-lgb * da) : 0.f);
;       const float wb = (db_ >= 0.f ? __builtin_amdgcn_exp2f(lgf * db_) : 0.f) + (db_ <= 0.f ? __builtin_amdgcn_exp2f(-lgb * db_) : 0.f);
;       p0[r] *= wa * SCALE; p1[r] *= wb * SCALE; }
	v_mul_f32_e32 v69, v69, v85
	v_add_u32_e32 v85, -8, v167
	v_cvt_f32_i32_e32 v169, v85
	v_subrev_u32_e32 v170, 40, v167
	v_cvt_f32_i32_e32 v171, v170
	v_cmp_lt_i32_e32 vcc, -1, v85
	v_mul_f32_e32 v172, v147, v169
	v_exp_f32_e32 v172, v172
	s_nop 0
	v_cndmask_b32_e32 v172, 0, v172, vcc
	v_cmp_gt_i32_e32 vcc, 1, v85
	v_mul_f32_e64 v85, -v152, v169
	v_exp_f32_e32 v85, v85
	v_mul_f32_e32 v169, v147, v171
	v_exp_f32_e32 v169, v169
	v_cndmask_b32_e32 v85, 0, v85, vcc
	v_cmp_lt_i32_e32 vcc, -1, v170
	v_add_f32_e32 v85, v172, v85
	v_mul_f32_e32 v85, 0x3db504f3, v85
	v_cndmask_b32_e32 v169, 0, v169, vcc
	v_cmp_gt_i32_e32 vcc, 1, v170
	v_mul_f32_e64 v170, -v152, v171
	v_exp_f32_e32 v170, v170
	v_mul_f32_e32 v85, v85, v70
	v_cndmask_b32_e32 v170, 0, v170, vcc
	v_add_f32_e32 v169, v169, v170
	v_mul_f32_e32 v70, 0x3db504f3, v169
	v_mul_f32_e32 v70, v70, v86
	v_add_u32_e32 v86, -9, v167
	v_cvt_f32_i32_e32 v169, v86
	v_subrev_u32_e32 v170, 41, v167
	v_cvt_f32_i32_e32 v171, v170
	v_cmp_lt_i32_e32 vcc, -1, v86
	v_mul_f32_e32 v172, v147, v169
	v_exp_f32_e32 v172, v172
	s_nop 0
	v_cndmask_b32_e32 v172, 0, v172, vcc
	v_cmp_gt_i32_e32 vcc, 1, v86
	v_mul_f32_e64 v86, -v152, v169
	v_exp_f32_e32 v86, v86
	v_mul_f32_e32 v169, v147, v171
	v_exp_f32_e32 v169, v169
	v_cndmask_b32_e32 v86, 0, v86, vcc
	v_cmp_lt_i32_e32 vcc, -1, v170
	v_add_f32_e32 v86, v172, v86
	v_mul_f32_e32 v86, 0x3db504f3, v86
	v_cndmask_b32_e32 v169, 0, v169, vcc
	v_cmp_gt_i32_e32 vcc, 1, v170
	v_mul_f32_e64 v170, -v152, v171
	v_exp_f32_e32 v170, v170
	v_mul_f32_e32 v86, v86, v71
	v_cndmask_b32_e32 v170, 0, v170, vcc
	v_add_f32_e32 v169, v169, v170
	v_mul_f32_e32 v71, 0x3db504f3, v169
	v_mul_f32_e32 v71, v71, v87
	v_add_u32_e32 v87, -10, v167
	v_cvt_f32_i32_e32 v169, v87
	v_subrev_u32_e32 v170, 42, v167
	v_cvt_f32_i32_e32 v171, v170
	v_cmp_lt_i32_e32 vcc, -1, v87
	v_mul_f32_e32 v172, v147, v169
	v_exp_f32_e32 v172, v172
	s_nop 0
	v_cndmask_b32_e32 v172, 0, v172, vcc
	v_cmp_gt_i32_e32 vcc, 1, v87
	v_mul_f32_e64 v87, -v152, v169
	v_exp_f32_e32 v87, v87
	v_mul_f32_e32 v169, v147, v171
	v_exp_f32_e32 v169, v169
	v_cndmask_b32_e32 v87, 0, v87, vcc
	v_cmp_lt_i32_e32 vcc, -1, v170
	v_add_f32_e32 v87, v172, v87
	v_mul_f32_e32 v87, 0x3db504f3, v87
	v_cndmask_b32_e32 v169, 0, v169, vcc
	v_cmp_gt_i32_e32 vcc, 1, v170
	v_mul_f32_e64 v170, -v152, v171
	v_exp_f32_e32 v170, v170
	v_mul_f32_e32 v87, v87, v72
	v_cndmask_b32_e32 v170, 0, v170, vcc
	v_add_f32_e32 v169, v169, v170
	v_mul_f32_e32 v72, 0x3db504f3, v169
	v_mul_f32_e32 v72, v72, v88
	v_add_u32_e32 v88, -11, v167
	v_cvt_f32_i32_e32 v169, v88
	v_subrev_u32_e32 v170, 43, v167
	v_cvt_f32_i32_e32 v171, v170
	v_cmp_lt_i32_e32 vcc, -1, v88
	v_mul_f32_e32 v172, v147, v169
	v_exp_f32_e32 v172, v172
	s_nop 0
	v_cndmask_b32_e32 v172, 0, v172, vcc
	v_cmp_gt_i32_e32 vcc, 1, v88
	v_mul_f32_e64 v88, -v152, v169
	v_exp_f32_e32 v88, v88
	v_mul_f32_e32 v169, v147, v171
	v_exp_f32_e32 v169, v169
	v_cndmask_b32_e32 v88, 0, v88, vcc
	v_cmp_lt_i32_e32 vcc, -1, v170
	v_add_f32_e32 v88, v172, v88
	v_mul_f32_e32 v88, 0x3db504f3, v88
	v_cndmask_b32_e32 v169, 0, v169, vcc
	v_cmp_gt_i32_e32 vcc, 1, v170
	v_mul_f32_e64 v170, -v152, v171
	v_exp_f32_e32 v170, v170
	v_mul_f32_e32 v88, v88, v73
	v_cndmask_b32_e32 v170, 0, v170, vcc
	v_add_f32_e32 v169, v169, v170
	v_mul_f32_e32 v73, 0x3db504f3, v169
	v_mul_f32_e32 v73, v73, v89
	v_add_u32_e32 v89, -16, v167
	v_cvt_f32_i32_e32 v169, v89
	v_subrev_u32_e32 v170, 48, v167
	v_cvt_f32_i32_e32 v171, v170
	v_cmp_lt_i32_e32 vcc, -1, v89
	v_mul_f32_e32 v172, v147, v169
	v_exp_f32_e32 v172, v172
	s_nop 0
	v_cndmask_b32_e32 v172, 0, v172, vcc
	v_cmp_gt_i32_e32 vcc, 1, v89
	v_mul_f32_e64 v89, -v152, v169
	v_exp_f32_e32 v89, v89
	v_mul_f32_e32 v169, v147, v171
	v_exp_f32_e32 v169, v169
	v_cndmask_b32_e32 v89, 0, v89, vcc
	v_cmp_lt_i32_e32 vcc, -1, v170
	v_add_f32_e32 v89, v172, v89
	v_mul_f32_e32 v89, 0x3db504f3, v89
	v_cndmask_b32_e32 v169, 0, v169, vcc
	v_cmp_gt_i32_e32 vcc, 1, v170
	v_mul_f32_e64 v170, -v152, v171
	v_exp_f32_e32 v170, v170
	v_mul_f32_e32 v89, v89, v74
	v_cndmask_b32_e32 v170, 0, v170, vcc
	v_add_f32_e32 v169, v169, v170
	v_mul_f32_e32 v74, 0x3db504f3, v169
	v_mul_f32_e32 v74, v74, v90
	v_subrev_u32_e32 v90, 17, v167
	v_cvt_f32_i32_e32 v169, v90
	v_subrev_u32_e32 v170, 49, v167
	v_cvt_f32_i32_e32 v171, v170
	v_cmp_lt_i32_e32 vcc, -1, v90
	v_mul_f32_e32 v172, v147, v169
	v_exp_f32_e32 v172, v172
	s_nop 0
	v_cndmask_b32_e32 v172, 0, v172, vcc
	v_cmp_gt_i32_e32 vcc, 1, v90
	v_mul_f32_e64 v90, -v152, v169
	v_exp_f32_e32 v90, v90
	v_mul_f32_e32 v169, v147, v171
	v_exp_f32_e32 v169, v169
	v_cndmask_b32_e32 v90, 0, v90, vcc
	v_cmp_lt_i32_e32 vcc, -1, v170
	v_add_f32_e32 v90, v172, v90
	v_mul_f32_e32 v90, 0x3db504f3, v90
	v_cndmask_b32_e32 v169, 0, v169, vcc
	v_cmp_gt_i32_e32 vcc, 1, v170
	v_mul_f32_e64 v170, -v152, v171
	v_exp_f32_e32 v170, v170
	v_mul_f32_e32 v90, v90, v75
	v_cndmask_b32_e32 v170, 0, v170, vcc
	v_add_f32_e32 v169, v169, v170
	v_mul_f32_e32 v75, 0x3db504f3, v169
	v_mul_f32_e32 v75, v75, v91
	v_subrev_u32_e32 v91, 18, v167
	v_cvt_f32_i32_e32 v169, v91
	v_subrev_u32_e32 v170, 50, v167
	v_cvt_f32_i32_e32 v171, v170
	v_cmp_lt_i32_e32 vcc, -1, v91
	v_mul_f32_e32 v172, v147, v169
	v_exp_f32_e32 v172, v172
	s_nop 0
	v_cndmask_b32_e32 v172, 0, v172, vcc
	v_cmp_gt_i32_e32 vcc, 1, v91
	v_mul_f32_e64 v91, -v152, v169
	v_exp_f32_e32 v91, v91
	v_mul_f32_e32 v169, v147, v171
	v_exp_f32_e32 v169, v169
	v_cndmask_b32_e32 v91, 0, v91, vcc
	v_cmp_lt_i32_e32 vcc, -1, v170
	v_add_f32_e32 v91, v172, v91
	v_mul_f32_e32 v91, 0x3db504f3, v91
	v_cndmask_b32_e32 v169, 0, v169, vcc
	v_cmp_gt_i32_e32 vcc, 1, v170
	v_mul_f32_e64 v170, -v152, v171
; #define SBAR() __builtin_amdgcn_sched_barrier(0)
; __device__ __forceinline__ int crow(int r, int hi) { return (r & 3) + 8 * (r >> 2) + 4 * hi; }
; template <int D0> __device__ __forceinline__ void pv_one(f32x16& od, int vb, bf16x8 pa0, bf16x8 pa1, bf16x8 pa2, bf16x8 pa3) {
;   const s16x4 l0 = tr_read<v_rd_off(D0, 0, 0)>(vb), h0 = tr_read<v_rd_off(D0, 0, 1)>(vb), l1 = tr_read<v_rd_off(D0, 1, 0)>(vb), h1 = tr_read<v_rd_off(D0, 1, 1)>(vb);
;   const s16x4 l2 = tr_read<v_rd_off(D0, 2, 0)>(vb), h2 = tr_read<v_rd_off(D0, 2, 1)>(vb), l3 = tr_read<v_rd_off(D0, 3, 0)>(vb), h3 = tr_read<v_rd_off(D0, 3, 1)>(vb);
;   asm volatile("s_waitcnt lgkmcnt(0)" ::: "memory"); SBAR();
;   od = __builtin_amdgcn_mfma_f32_32x32x16_bf16(pa0, PKLH(l0, h0), od, 0, 0, 0);
;   od = __builtin_amdgcn_mfma_f32_32x32x16_bf16(pa1, PKLH(l1, h1), od, 0, 0, 0);
;   od = __builtin_amdgcn_mfma_f32_32x32x16_bf16(pa2, PKLH(l2, h2), od, 0, 0, 0);
;   od = __builtin_amdgcn_mfma_f32_32x32x16_bf16(pa3, PKLH(l3, h3), od, 0, 0, 0);
; __device__ __forceinline__ void ret_output_unit(const bf16* __restrict__ Rb, const bf16* __restrict__ Sf, const bf16* __restrict__ Sb, bf16* Y, long rowbase, int h, float lgf, float lgb, char* lds) {
;     ...
;     for (int r = 0; r < 16; ++r) {
;       const int ja = tile * 64 + crow(r, hi), jb = ja + 32; const float da = (float)(a - ja), db_ = (float)(a - jb);
;       const float wa = (da >= 0.f ? __builtin_amdgcn_exp2f(lgf * da) : 0.f) + (da <= 0.f ? __builtin_amdgcn_exp2f(-lgb * da) : 0.f);
;       const float wb = (db_ >= 0.f ? __builtin_amdgcn_exp2f(lgf * db_) : 0.f) + (db_ <= 0.f ? __builtin_amdgcn_exp2f(-lgb * db_) : 0.f);
;       p0[r] *= wa * SCALE; p1[r] *= wb * SCALE; }
;     bf16x8 pa0, pa1, pa2, pa3; PK4(p0, 0, pa0); PK4(p0, 8, pa1); PK4(p1, 0, pa2); PK4(p1, 8, pa3);
	v_exp_f32_e32 v170, v170
	v_mul_f32_e32 v91, v91, v76
	v_cndmask_b32_e32 v170, 0, v170, vcc
	v_add_f32_e32 v169, v169, v170
	v_mul_f32_e32 v76, 0x3db504f3, v169
	v_mul_f32_e32 v92, v76, v92
	v_subrev_u32_e32 v76, 19, v167
	v_cvt_f32_i32_e32 v169, v76
	v_subrev_u32_e32 v170, 51, v167
	v_cvt_f32_i32_e32 v171, v170
	v_cmp_lt_i32_e32 vcc, -1, v76
	v_mul_f32_e32 v172, v147, v169
	v_exp_f32_e32 v172, v172
	s_nop 0
	v_cndmask_b32_e32 v172, 0, v172, vcc
	v_cmp_gt_i32_e32 vcc, 1, v76
	v_mul_f32_e64 v76, -v152, v169
	v_exp_f32_e32 v76, v76
	v_mul_f32_e32 v169, v147, v171
	v_exp_f32_e32 v169, v169
	v_cndmask_b32_e32 v76, 0, v76, vcc
	v_cmp_lt_i32_e32 vcc, -1, v170
	v_add_f32_e32 v76, v172, v76
	v_mul_f32_e32 v76, 0x3db504f3, v76
	v_cndmask_b32_e32 v169, 0, v169, vcc
	v_cmp_gt_i32_e32 vcc, 1, v170
	v_mul_f32_e64 v170, -v152, v171
	v_exp_f32_e32 v170, v170
	s_nop 0
	v_cndmask_b32_e32 v170, 0, v170, vcc
	v_add_f32_e32 v169, v169, v170
	v_mul_f32_e32 v170, v76, v77
	v_mul_f32_e32 v76, 0x3db504f3, v169
	v_mul_f32_e32 v93, v76, v93
	v_subrev_u32_e32 v76, 24, v167
	v_cvt_f32_i32_e32 v77, v76
	v_subrev_u32_e32 v169, 56, v167
	v_cvt_f32_i32_e32 v171, v169
	v_cmp_lt_i32_e32 vcc, -1, v76
	v_mul_f32_e32 v172, v147, v77
	v_exp_f32_e32 v172, v172
	s_nop 0
	v_cndmask_b32_e32 v172, 0, v172, vcc
	v_cmp_gt_i32_e32 vcc, 1, v76
	v_mul_f32_e64 v76, -v152, v77
	v_exp_f32_e32 v76, v76
	v_mul_f32_e32 v77, v147, v171
	v_exp_f32_e32 v77, v77
	v_cndmask_b32_e32 v76, 0, v76, vcc
	v_cmp_lt_i32_e32 vcc, -1, v169
	v_add_f32_e32 v76, v172, v76
	v_mul_f32_e32 v76, 0x3db504f3, v76
	v_cndmask_b32_e32 v77, 0, v77, vcc
	v_cmp_gt_i32_e32 vcc, 1, v169
	v_mul_f32_e64 v169, -v152, v171
	v_exp_f32_e32 v169, v169
	s_nop 0
	v_cndmask_b32_e32 v169, 0, v169, vcc
	v_add_f32_e32 v77, v77, v169
	v_mul_f32_e32 v169, v76, v78
	v_mul_f32_e32 v76, 0x3db504f3, v77
	v_mul_f32_e32 v94, v76, v94
	v_subrev_u32_e32 v76, 25, v167
	v_cvt_f32_i32_e32 v77, v76
	v_subrev_u32_e32 v78, 57, v167
	v_cvt_f32_i32_e32 v171, v78
	v_cmp_lt_i32_e32 vcc, -1, v76
	v_mul_f32_e32 v172, v147, v77
	v_exp_f32_e32 v172, v172
	s_nop 0
	v_cndmask_b32_e32 v172, 0, v172, vcc
	v_cmp_gt_i32_e32 vcc, 1, v76
	v_mul_f32_e64 v76, -v152, v77
	v_exp_f32_e32 v76, v76
	v_mul_f32_e32 v77, v147, v171
	v_exp_f32_e32 v77, v77
	v_cndmask_b32_e32 v76, 0, v76, vcc
	v_cmp_lt_i32_e32 vcc, -1, v78
	v_add_f32_e32 v76, v172, v76
	v_mul_f32_e32 v76, 0x3db504f3, v76
	v_cndmask_b32_e32 v77, 0, v77, vcc
	v_cmp_gt_i32_e32 vcc, 1, v78
	v_mul_f32_e64 v78, -v152, v171
	v_exp_f32_e32 v78, v78
	v_mul_f32_e32 v171, v76, v79
	v_cndmask_b32_e32 v78, 0, v78, vcc
	v_add_f32_e32 v77, v77, v78
	v_mul_f32_e32 v76, 0x3db504f3, v77
	v_mul_f32_e32 v95, v76, v95
	v_subrev_u32_e32 v76, 26, v167
	v_cvt_f32_i32_e32 v77, v76
	v_subrev_u32_e32 v78, 58, v167
	v_cvt_f32_i32_e32 v79, v78
	v_cmp_lt_i32_e32 vcc, -1, v76
	v_mul_f32_e32 v172, v147, v77
	v_exp_f32_e32 v172, v172
	s_nop 0
	v_cndmask_b32_e32 v172, 0, v172, vcc
	v_cmp_gt_i32_e32 vcc, 1, v76
	v_mul_f32_e64 v76, -v152, v77
	v_exp_f32_e32 v76, v76
	v_mul_f32_e32 v77, v147, v79
	v_exp_f32_e32 v77, v77
	v_cndmask_b32_e32 v76, 0, v76, vcc
	v_cmp_lt_i32_e32 vcc, -1, v78
	v_add_f32_e32 v76, v172, v76
	v_mul_f32_e32 v76, 0x3db504f3, v76
	v_cndmask_b32_e32 v77, 0, v77, vcc
	v_cmp_gt_i32_e32 vcc, 1, v78
	v_mul_f32_e64 v78, -v152, v79
	v_exp_f32_e32 v78, v78
	v_mul_f32_e32 v172, v76, v80
	v_cndmask_b32_e32 v78, 0, v78, vcc
	v_add_f32_e32 v77, v77, v78
	v_mul_f32_e32 v76, 0x3db504f3, v77
	v_mul_f32_e32 v96, v76, v96
	v_subrev_u32_e32 v76, 27, v167
	v_cvt_f32_i32_e32 v77, v76
	v_subrev_u32_e32 v78, 59, v167
	v_cvt_f32_i32_e32 v79, v78
	v_cmp_lt_i32_e32 vcc, -1, v76
	v_mul_f32_e32 v80, v147, v77
	v_exp_f32_e32 v80, v80
	s_nop 0
	v_cndmask_b32_e32 v80, 0, v80, vcc
	v_cmp_gt_i32_e32 vcc, 1, v76
	v_mul_f32_e64 v76, -v152, v77
	v_exp_f32_e32 v76, v76
	v_mul_f32_e32 v77, v147, v79
	v_exp_f32_e32 v77, v77
	v_cndmask_b32_e32 v76, 0, v76, vcc
	v_cmp_lt_i32_e32 vcc, -1, v78
	v_add_f32_e32 v76, v80, v76
	v_mul_f32_e32 v76, 0x3db504f3, v76
	v_cndmask_b32_e32 v77, 0, v77, vcc
	v_cmp_gt_i32_e32 vcc, 1, v78
	v_mul_f32_e64 v78, -v152, v79
	v_exp_f32_e32 v78, v78
	v_mul_f32_e32 v167, v76, v81
	v_cndmask_b32_e32 v78, 0, v78, vcc
	v_add_f32_e32 v77, v77, v78
	v_mul_f32_e32 v76, 0x3db504f3, v77
	v_mul_f32_e32 v97, v76, v97
	v_cvt_pk_bf16_f32 v76, v168, v82
	v_cvt_pk_bf16_f32 v77, v83, v84
	v_cvt_pk_bf16_f32 v78, v85, v86
	v_cvt_pk_bf16_f32 v79, v87, v88
	v_cvt_pk_bf16_f32 v80, v89, v90
	v_cvt_pk_bf16_f32 v81, v91, v170
	v_cvt_pk_bf16_f32 v82, v169, v171
	v_cvt_pk_bf16_f32 v83, v172, v167
	v_cvt_pk_bf16_f32 v66, v66, v67
	v_cvt_pk_bf16_f32 v67, v68, v69
	v_cvt_pk_bf16_f32 v68, v70, v71
	v_cvt_pk_bf16_f32 v69, v72, v73
	v_cvt_pk_bf16_f32 v70, v74, v75
	v_cvt_pk_bf16_f32 v71, v92, v93
	v_cvt_pk_bf16_f32 v72, v94, v95
	v_cvt_pk_bf16_f32 v73, v96, v97
	ds_read_b64_tr_b16 v[84:85], v153 offset:0
	ds_read_b64_tr_b16 v[86:87], v153 offset:0x800
	ds_read_b64_tr_b16 v[88:89], v153 offset:0x1000
	ds_read_b64_tr_b16 v[90:91], v153 offset:0x1800
	ds_read_b64_tr_b16 v[92:93], v153 offset:0x2000
	ds_read_b64_tr_b16 v[94:95], v153 offset:0x2800
	ds_read_b64_tr_b16 v[168:169], v153 offset:0x3000
	ds_read_b64_tr_b16 v[170:171], v153 offset:0x3800
	s_waitcnt lgkmcnt(0)
; #define SBAR() __builtin_amdgcn_sched_barrier(0)
; __device__ __forceinline__ int crow(int r, int hi) { return (r & 3) + 8 * (r >> 2) + 4 * hi; }
; template <int D0> __device__ __forceinline__ void pv_one(f32x16& od, int vb, bf16x8 pa0, bf16x8 pa1, bf16x8 pa2, bf16x8 pa3) {
;   const s16x4 l0 = tr_read<v_rd_off(D0, 0, 0)>(vb), h0 = tr_read<v_rd_off(D0, 0, 1)>(vb), l1 = tr_read<v_rd_off(D0, 1, 0)>(vb), h1 = tr_read<v_rd_off(D0, 1, 1)>(vb);
;   const s16x4 l2 = tr_read<v_rd_off(D0, 2, 0)>(vb), h2 = tr_read<v_rd_off(D0, 2, 1)>(vb), l3 = tr_read<v_rd_off(D0, 3, 0)>(vb), h3 = tr_read<v_rd_off(D0, 3, 1)>(vb);
;   asm volatile("s_waitcnt lgkmcnt(0)" ::: "memory"); SBAR();
;   od = __builtin_amdgcn_mfma_f32_32x32x16_bf16(pa0, PKLH(l0, h0), od, 0, 0, 0);
;   od = __builtin_amdgcn_mfma_f32_32x32x16_bf16(pa1, PKLH(l1, h1), od, 0, 0, 0);
;   od = __builtin_amdgcn_mfma_f32_32x32x16_bf16(pa2, PKLH(l2, h2), od, 0, 0, 0);
;   od = __builtin_amdgcn_mfma_f32_32x32x16_bf16(pa3, PKLH(l3, h3), od, 0, 0, 0);
; __device__ __forceinline__ void ret_output_unit(const bf16* __restrict__ Rb, const bf16* __restrict__ Sf, const bf16* __restrict__ Sb, bf16* Y, long rowbase, int h, float lgf, float lgb, char* lds) {
;     ...
;   const bf16* Gp = Rb + (rowbase + wid * QBLK) * 2048 + 1536 + h * 128; bf16* Yp = Y + (rowbase + wid * QBLK) * 512 + h * 128;
;   unsigned short gq[16][4];
; #pragma unroll
;   for (int r = 0; r < 16; ++r)
; #pragma unroll
;     for (int eb = 0; eb < 4; ++eb) gq[r][eb] = Gp[(long)crow(r, hi) * 2048 + 32 * eb + r32];
; #pragma unroll
;   for (int r = 0; r < 16; ++r) {
;     float ss = o[0][r] * o[0][r] + o[1][r] * o[1][r] + o[2][r] * o[2][r] + o[3][r] * o[3][r];
;     ss = half32_sum(ss);
	s_nop 0
	v_permlane32_swap_b32_e32 v76, v78
	v_permlane32_swap_b32_e32 v77, v79
	v_permlane32_swap_b32_e32 v80, v82
	v_permlane32_swap_b32_e32 v81, v83
	v_permlane32_swap_b32_e32 v66, v68
	v_permlane32_swap_b32_e32 v67, v69
	v_permlane32_swap_b32_e32 v70, v72
	v_permlane32_swap_b32_e32 v71, v73
	v_mfma_f32_32x32x16_bf16 v[50:65], v[76:79], v[84:87], v[50:65]
	ds_read_b64_tr_b16 v[84:85], v153 offset:0x200
	ds_read_b64_tr_b16 v[86:87], v153 offset:0xa00
	v_mfma_f32_32x32x16_bf16 v[50:65], v[80:83], v[88:91], v[50:65]
	ds_read_b64_tr_b16 v[88:89], v153 offset:0x1200
	ds_read_b64_tr_b16 v[90:91], v153 offset:0x1a00
	v_mfma_f32_32x32x16_bf16 v[50:65], v[66:69], v[92:95], v[50:65]
	ds_read_b64_tr_b16 v[92:93], v153 offset:0x2200
	ds_read_b64_tr_b16 v[94:95], v153 offset:0x2a00
	v_mfma_f32_32x32x16_bf16 v[50:65], v[70:73], v[168:171], v[50:65]
	ds_read_b64_tr_b16 v[168:169], v153 offset:0x3200
	ds_read_b64_tr_b16 v[170:171], v153 offset:0x3a00
	s_waitcnt lgkmcnt(0)
	v_mfma_f32_32x32x16_bf16 v[34:49], v[76:79], v[84:87], v[34:49]
	ds_read_b64_tr_b16 v[84:85], v153 offset:0x400
	ds_read_b64_tr_b16 v[86:87], v153 offset:0xc00
	v_mfma_f32_32x32x16_bf16 v[34:49], v[80:83], v[88:91], v[34:49]
	ds_read_b64_tr_b16 v[88:89], v153 offset:0x1400
	ds_read_b64_tr_b16 v[90:91], v153 offset:0x1c00
	v_mfma_f32_32x32x16_bf16 v[34:49], v[66:69], v[92:95], v[34:49]
	ds_read_b64_tr_b16 v[92:93], v153 offset:0x2400
	ds_read_b64_tr_b16 v[94:95], v153 offset:0x2c00
	v_mfma_f32_32x32x16_bf16 v[34:49], v[70:73], v[168:171], v[34:49]
	ds_read_b64_tr_b16 v[168:169], v153 offset:0x3400
	ds_read_b64_tr_b16 v[170:171], v153 offset:0x3c00
	s_waitcnt lgkmcnt(0)
	v_mfma_f32_32x32x16_bf16 v[18:33], v[76:79], v[84:87], v[18:33]
	ds_read_b64_tr_b16 v[84:85], v153 offset:0x600
	ds_read_b64_tr_b16 v[86:87], v153 offset:0xe00
	v_mfma_f32_32x32x16_bf16 v[18:33], v[80:83], v[88:91], v[18:33]
	ds_read_b64_tr_b16 v[88:89], v153 offset:0x1600
	ds_read_b64_tr_b16 v[90:91], v153 offset:0x1e00
	v_mfma_f32_32x32x16_bf16 v[18:33], v[66:69], v[92:95], v[18:33]
	ds_read_b64_tr_b16 v[92:93], v153 offset:0x2600
	ds_read_b64_tr_b16 v[94:95], v153 offset:0x2e00
	v_mfma_f32_32x32x16_bf16 v[18:33], v[70:73], v[168:171], v[18:33]
	ds_read_b64_tr_b16 v[168:169], v153 offset:0x3600
	ds_read_b64_tr_b16 v[170:171], v153 offset:0x3e00
	s_waitcnt lgkmcnt(0)
	v_mfma_f32_32x32x16_bf16 v[2:17], v[76:79], v[84:87], v[2:17]
	s_sub_i32 s11, s11, 64
	v_lshl_add_u64 v[148:149], v[148:149], 0, s[54:55]
	s_cmpk_lg_i32 s11, 0xff00
	s_barrier
	v_mfma_f32_32x32x16_bf16 v[2:17], v[80:83], v[88:91], v[2:17]
	v_mfma_f32_32x32x16_bf16 v[2:17], v[66:69], v[92:95], v[2:17]
	v_mfma_f32_32x32x16_bf16 v[2:17], v[70:73], v[168:171], v[2:17]
	s_cbranch_scc1 .LBB0_1005
	v_lshl_add_u32 v130, v150, 5, v151
	v_lshlrev_b32_e32 v131, 8, v146
	v_lshlrev_b32_e32 v132, 10, v150
	v_lshl_add_u32 v132, v151, 1, v132
	v_add_u32_e32 v132, v132, v131
	v_lshl_add_u32 v133, v130, 4, v131
	s_lshl_b32 s16, s10, 1
	v_lshrrev_b32_e32 v129, 4, v130
	v_add_u32_e32 v129, v129, v146
	v_add_u32_e32 v129, s8, v129
	v_and_b32_e32 v128, 15, v130
	v_lshlrev_b32_e32 v128, 4, v128
	v_add_u32_e32 v128, s16, v128
	v_lshl_add_u32 v147, v129, 12, v128
	v_lshl_add_u32 v186, v129, 10, v128
	global_load_dwordx4 v[66:69], v147, s[92:93] offset:3072
	v_add_u32_e32 v147, 0x4000, v147
	global_load_dwordx4 v[70:73], v147, s[92:93] offset:3072
	v_add_u32_e32 v147, 0x4000, v147
	global_load_dwordx4 v[74:77], v147, s[92:93] offset:3072
	v_add_u32_e32 v147, 0x4000, v147
	global_load_dwordx4 v[78:81], v147, s[92:93] offset:3072
	v_add_u32_e32 v147, 0x4000, v147
	global_load_dwordx4 v[82:85], v147, s[92:93] offset:3072
	v_add_u32_e32 v147, 0x4000, v147
	global_load_dwordx4 v[86:89], v147, s[92:93] offset:3072
	v_add_u32_e32 v147, 0x4000, v147
	global_load_dwordx4 v[90:93], v147, s[92:93] offset:3072
	v_add_u32_e32 v147, 0x4000, v147
	global_load_dwordx4 v[94:97], v147, s[92:93] offset:3072
	v_mul_f32_e32 v98, v34, v34
	v_fmac_f32_e32 v98, v50, v50
	v_fmac_f32_e32 v98, v18, v18
	v_fmac_f32_e32 v98, v2, v2
	v_mul_f32_e32 v99, v35, v35
	v_fmac_f32_e32 v99, v51, v51
	v_fmac_f32_e32 v99, v19, v19
	v_fmac_f32_e32 v99, v3, v3
	v_mul_f32_e32 v100, v36, v36
	v_fmac_f32_e32 v100, v52, v52
	v_fmac_f32_e32 v100, v20, v20
	v_fmac_f32_e32 v100, v4, v4
	v_mul_f32_e32 v101, v37, v37
	v_fmac_f32_e32 v101, v53, v53
	v_fmac_f32_e32 v101, v21, v21
	v_fmac_f32_e32 v101, v5, v5
	v_mul_f32_e32 v102, v38, v38
	v_fmac_f32_e32 v102, v54, v54
	v_fmac_f32_e32 v102, v22, v22
	v_fmac_f32_e32 v102, v6, v6
	v_mul_f32_e32 v103, v39, v39
	v_fmac_f32_e32 v103, v55, v55
	v_fmac_f32_e32 v103, v23, v23
	v_fmac_f32_e32 v103, v7, v7
	v_mul_f32_e32 v104, v40, v40
	v_fmac_f32_e32 v104, v56, v56
	v_fmac_f32_e32 v104, v24, v24
	v_fmac_f32_e32 v104, v8, v8
	v_mul_f32_e32 v105, v41, v41
	v_fmac_f32_e32 v105, v57, v57
	v_fmac_f32_e32 v105, v25, v25
	v_fmac_f32_e32 v105, v9, v9
	v_mul_f32_e32 v106, v42, v42
	v_fmac_f32_e32 v106, v58, v58
	v_fmac_f32_e32 v106, v26, v26
	v_fmac_f32_e32 v106, v10, v10
	v_mul_f32_e32 v107, v43, v43
	v_fmac_f32_e32 v107, v59, v59
	v_fmac_f32_e32 v107, v27, v27
	v_fmac_f32_e32 v107, v11, v11
	v_mul_f32_e32 v108, v44, v44
	v_fmac_f32_e32 v108, v60, v60
	v_fmac_f32_e32 v108, v28, v28
	v_fmac_f32_e32 v108, v12, v12
	v_mul_f32_e32 v109, v45, v45
	v_fmac_f32_e32 v109, v61, v61
	v_fmac_f32_e32 v109, v29, v29
	v_fmac_f32_e32 v109, v13, v13
	v_mul_f32_e32 v110, v46, v46
	v_fmac_f32_e32 v110, v62, v62
	v_fmac_f32_e32 v110, v30, v30
	v_fmac_f32_e32 v110, v14, v14
	v_mul_f32_e32 v111, v47, v47
	v_fmac_f32_e32 v111, v63, v63
	v_fmac_f32_e32 v111, v31, v31
	v_fmac_f32_e32 v111, v15, v15
	v_mul_f32_e32 v112, v48, v48
; __device__ __forceinline__ int crow(int r, int hi) { return (r & 3) + 8 * (r >> 2) + 4 * hi; }
; template <int CTRL> __device__ __forceinline__ float dppf(float x) { return __builtin_bit_cast(float, __builtin_amdgcn_mov_dpp(__builtin_bit_cast(int, x), CTRL, 0xf, 0xf, true)); }
; __device__ __forceinline__ float half32_sum(float x) {
;   x += dppf<0xB1>(x); x += dppf<0x4E>(x); x += dppf<0x124>(x); x += dppf<0x128>(x);
;   auto s = __builtin_amdgcn_permlane16_swap(__float_as_uint(x), __float_as_uint(x), false, false);
;   return __uint_as_float(s[0]) + __uint_as_float(s[1]);
; }
; __device__ __forceinline__ void ret_output_unit(const bf16* __restrict__ Rb, const bf16* __restrict__ Sf, const bf16* __restrict__ Sb, bf16* Y, long rowbase, int h, float lgf, float lgb, char* lds) {
;     ...
;   for (int r = 0; r < 16; ++r) {
;     float ss = o[0][r] * o[0][r] + o[1][r] * o[1][r] + o[2][r] * o[2][r] + o[3][r] * o[3][r];
;     ss = half32_sum(ss);
;     const float rs = __builtin_amdgcn_rsqf(ss * (1.0f / 128.0f) + 1e-6f); const int row = crow(r, hi);
	v_fmac_f32_e32 v112, v64, v64
	v_fmac_f32_e32 v112, v32, v32
	v_fmac_f32_e32 v112, v16, v16
	v_mul_f32_e32 v113, v49, v49
	v_fmac_f32_e32 v113, v65, v65
	v_fmac_f32_e32 v113, v33, v33
	v_fmac_f32_e32 v113, v17, v17
	v_add_f32_dpp v98, v98, v98 quad_perm:[1,0,3,2] row_mask:0xf bank_mask:0xf bound_ctrl:1
	v_add_f32_dpp v99, v99, v99 quad_perm:[1,0,3,2] row_mask:0xf bank_mask:0xf bound_ctrl:1
	v_add_f32_dpp v100, v100, v100 quad_perm:[1,0,3,2] row_mask:0xf bank_mask:0xf bound_ctrl:1
	v_add_f32_dpp v101, v101, v101 quad_perm:[1,0,3,2] row_mask:0xf bank_mask:0xf bound_ctrl:1
	v_add_f32_dpp v102, v102, v102 quad_perm:[1,0,3,2] row_mask:0xf bank_mask:0xf bound_ctrl:1
	v_add_f32_dpp v103, v103, v103 quad_perm:[1,0,3,2] row_mask:0xf bank_mask:0xf bound_ctrl:1
	v_add_f32_dpp v104, v104, v104 quad_perm:[1,0,3,2] row_mask:0xf bank_mask:0xf bound_ctrl:1
	v_add_f32_dpp v105, v105, v105 quad_perm:[1,0,3,2] row_mask:0xf bank_mask:0xf bound_ctrl:1
	v_add_f32_dpp v106, v106, v106 quad_perm:[1,0,3,2] row_mask:0xf bank_mask:0xf bound_ctrl:1
	v_add_f32_dpp v107, v107, v107 quad_perm:[1,0,3,2] row_mask:0xf bank_mask:0xf bound_ctrl:1
	v_add_f32_dpp v108, v108, v108 quad_perm:[1,0,3,2] row_mask:0xf bank_mask:0xf bound_ctrl:1
	v_add_f32_dpp v109, v109, v109 quad_perm:[1,0,3,2] row_mask:0xf bank_mask:0xf bound_ctrl:1
	v_add_f32_dpp v110, v110, v110 quad_perm:[1,0,3,2] row_mask:0xf bank_mask:0xf bound_ctrl:1
	v_add_f32_dpp v111, v111, v111 quad_perm:[1,0,3,2] row_mask:0xf bank_mask:0xf bound_ctrl:1
	v_add_f32_dpp v112, v112, v112 quad_perm:[1,0,3,2] row_mask:0xf bank_mask:0xf bound_ctrl:1
	v_add_f32_dpp v113, v113, v113 quad_perm:[1,0,3,2] row_mask:0xf bank_mask:0xf bound_ctrl:1
	v_add_f32_dpp v98, v98, v98 quad_perm:[2,3,0,1] row_mask:0xf bank_mask:0xf bound_ctrl:1
	v_add_f32_dpp v99, v99, v99 quad_perm:[2,3,0,1] row_mask:0xf bank_mask:0xf bound_ctrl:1
	v_add_f32_dpp v100, v100, v100 quad_perm:[2,3,0,1] row_mask:0xf bank_mask:0xf bound_ctrl:1
	v_add_f32_dpp v101, v101, v101 quad_perm:[2,3,0,1] row_mask:0xf bank_mask:0xf bound_ctrl:1
	v_add_f32_dpp v102, v102, v102 quad_perm:[2,3,0,1] row_mask:0xf bank_mask:0xf bound_ctrl:1
	v_add_f32_dpp v103, v103, v103 quad_perm:[2,3,0,1] row_mask:0xf bank_mask:0xf bound_ctrl:1
	v_add_f32_dpp v104, v104, v104 quad_perm:[2,3,0,1] row_mask:0xf bank_mask:0xf bound_ctrl:1
	v_add_f32_dpp v105, v105, v105 quad_perm:[2,3,0,1] row_mask:0xf bank_mask:0xf bound_ctrl:1
	v_add_f32_dpp v106, v106, v106 quad_perm:[2,3,0,1] row_mask:0xf bank_mask:0xf bound_ctrl:1
	v_add_f32_dpp v107, v107, v107 quad_perm:[2,3,0,1] row_mask:0xf bank_mask:0xf bound_ctrl:1
	v_add_f32_dpp v108, v108, v108 quad_perm:[2,3,0,1] row_mask:0xf bank_mask:0xf bound_ctrl:1
	v_add_f32_dpp v109, v109, v109 quad_perm:[2,3,0,1] row_mask:0xf bank_mask:0xf bound_ctrl:1
	v_add_f32_dpp v110, v110, v110 quad_perm:[2,3,0,1] row_mask:0xf bank_mask:0xf bound_ctrl:1
	v_add_f32_dpp v111, v111, v111 quad_perm:[2,3,0,1] row_mask:0xf bank_mask:0xf bound_ctrl:1
	v_add_f32_dpp v112, v112, v112 quad_perm:[2,3,0,1] row_mask:0xf bank_mask:0xf bound_ctrl:1
	v_add_f32_dpp v113, v113, v113 quad_perm:[2,3,0,1] row_mask:0xf bank_mask:0xf bound_ctrl:1
	v_add_f32_dpp v98, v98, v98 row_ror:4 row_mask:0xf bank_mask:0xf bound_ctrl:1
	v_add_f32_dpp v99, v99, v99 row_ror:4 row_mask:0xf bank_mask:0xf bound_ctrl:1
	v_add_f32_dpp v100, v100, v100 row_ror:4 row_mask:0xf bank_mask:0xf bound_ctrl:1
	v_add_f32_dpp v101, v101, v101 row_ror:4 row_mask:0xf bank_mask:0xf bound_ctrl:1
	v_add_f32_dpp v102, v102, v102 row_ror:4 row_mask:0xf bank_mask:0xf bound_ctrl:1
	v_add_f32_dpp v103, v103, v103 row_ror:4 row_mask:0xf bank_mask:0xf bound_ctrl:1
	v_add_f32_dpp v104, v104, v104 row_ror:4 row_mask:0xf bank_mask:0xf bound_ctrl:1
	v_add_f32_dpp v105, v105, v105 row_ror:4 row_mask:0xf bank_mask:0xf bound_ctrl:1
	v_add_f32_dpp v106, v106, v106 row_ror:4 row_mask:0xf bank_mask:0xf bound_ctrl:1
	v_add_f32_dpp v107, v107, v107 row_ror:4 row_mask:0xf bank_mask:0xf bound_ctrl:1
	v_add_f32_dpp v108, v108, v108 row_ror:4 row_mask:0xf bank_mask:0xf bound_ctrl:1
	v_add_f32_dpp v109, v109, v109 row_ror:4 row_mask:0xf bank_mask:0xf bound_ctrl:1
	v_add_f32_dpp v110, v110, v110 row_ror:4 row_mask:0xf bank_mask:0xf bound_ctrl:1
	v_add_f32_dpp v111, v111, v111 row_ror:4 row_mask:0xf bank_mask:0xf bound_ctrl:1
	v_add_f32_dpp v112, v112, v112 row_ror:4 row_mask:0xf bank_mask:0xf bound_ctrl:1
	v_add_f32_dpp v113, v113, v113 row_ror:4 row_mask:0xf bank_mask:0xf bound_ctrl:1
	v_add_f32_dpp v98, v98, v98 row_ror:8 row_mask:0xf bank_mask:0xf bound_ctrl:1
	v_add_f32_dpp v99, v99, v99 row_ror:8 row_mask:0xf bank_mask:0xf bound_ctrl:1
	v_add_f32_dpp v100, v100, v100 row_ror:8 row_mask:0xf bank_mask:0xf bound_ctrl:1
	v_add_f32_dpp v101, v101, v101 row_ror:8 row_mask:0xf bank_mask:0xf bound_ctrl:1
	v_add_f32_dpp v102, v102, v102 row_ror:8 row_mask:0xf bank_mask:0xf bound_ctrl:1
	v_add_f32_dpp v103, v103, v103 row_ror:8 row_mask:0xf bank_mask:0xf bound_ctrl:1
	v_add_f32_dpp v104, v104, v104 row_ror:8 row_mask:0xf bank_mask:0xf bound_ctrl:1
	v_add_f32_dpp v105, v105, v105 row_ror:8 row_mask:0xf bank_mask:0xf bound_ctrl:1
	v_add_f32_dpp v106, v106, v106 row_ror:8 row_mask:0xf bank_mask:0xf bound_ctrl:1
	v_add_f32_dpp v107, v107, v107 row_ror:8 row_mask:0xf bank_mask:0xf bound_ctrl:1
	v_add_f32_dpp v108, v108, v108 row_ror:8 row_mask:0xf bank_mask:0xf bound_ctrl:1
	v_add_f32_dpp v109, v109, v109 row_ror:8 row_mask:0xf bank_mask:0xf bound_ctrl:1
	v_add_f32_dpp v110, v110, v110 row_ror:8 row_mask:0xf bank_mask:0xf bound_ctrl:1
	v_add_f32_dpp v111, v111, v111 row_ror:8 row_mask:0xf bank_mask:0xf bound_ctrl:1
	v_add_f32_dpp v112, v112, v112 row_ror:8 row_mask:0xf bank_mask:0xf bound_ctrl:1
; __device__ __forceinline__ int crow(int r, int hi) { return (r & 3) + 8 * (r >> 2) + 4 * hi; }
; __device__ __forceinline__ float bf2f(unsigned short b) { return __uint_as_float(((unsigned)b) << 16); }
; __device__ __forceinline__ unsigned short f2bf(float f) { return (unsigned short)(cvtpk(f, 0.f) & 0xffffu); }
; template <int CTRL> __device__ __forceinline__ float dppf(float x) { return __builtin_bit_cast(float, __builtin_amdgcn_mov_dpp(__builtin_bit_cast(int, x), CTRL, 0xf, 0xf, true)); }
; __device__ __forceinline__ float half32_sum(float x) {
;   x += dppf<0xB1>(x); x += dppf<0x4E>(x); x += dppf<0x124>(x); x += dppf<0x128>(x);
;   auto s = __builtin_amdgcn_permlane16_swap(__float_as_uint(x), __float_as_uint(x), false, false);
;   return __uint_as_float(s[0]) + __uint_as_float(s[1]);
; }
; __device__ __forceinline__ void ret_output_unit(const bf16* __restrict__ Rb, const bf16* __restrict__ Sf, const bf16* __restrict__ Sb, bf16* Y, long rowbase, int h, float lgf, float lgb, char* lds) {
;     ...
;   const bf16* Gp = Rb + (rowbase + wid * QBLK) * 2048 + 1536 + h * 128; bf16* Yp = Y + (rowbase + wid * QBLK) * 512 + h * 128;
;   unsigned short gq[16][4];
; #pragma unroll
;   for (int r = 0; r < 16; ++r)
; #pragma unroll
;     for (int eb = 0; eb < 4; ++eb) gq[r][eb] = Gp[(long)crow(r, hi) * 2048 + 32 * eb + r32];
; #pragma unroll
;   for (int r = 0; r < 16; ++r) {
;     float ss = o[0][r] * o[0][r] + o[1][r] * o[1][r] + o[2][r] * o[2][r] + o[3][r] * o[3][r];
;     ss = half32_sum(ss);
;     const float rs = __builtin_amdgcn_rsqf(ss * (1.0f / 128.0f) + 1e-6f); const int row = crow(r, hi);
; #pragma unroll
;     for (int eb = 0; eb < 4; ++eb) { const float g = bf2f(gq[r][eb]);
;       const float sg = g * __builtin_amdgcn_rcpf(1.0f + __builtin_amdgcn_exp2f(-1.4426950408889634f * g));
;       Yp[(long)row * 512 + 32 * eb + r32] = f2bf(o[eb][r] * rs * sg); } }
	v_add_f32_dpp v113, v113, v113 row_ror:8 row_mask:0xf bank_mask:0xf bound_ctrl:1
	v_mov_b32_e32 v114, v98
	v_mov_b32_e32 v115, v99
	v_mov_b32_e32 v116, v100
	v_mov_b32_e32 v117, v101
	v_mov_b32_e32 v118, v102
	v_mov_b32_e32 v119, v103
	v_mov_b32_e32 v120, v104
	v_mov_b32_e32 v121, v105
	v_mov_b32_e32 v122, v106
	v_mov_b32_e32 v123, v107
	v_mov_b32_e32 v124, v108
	v_mov_b32_e32 v125, v109
	v_mov_b32_e32 v126, v110
	v_mov_b32_e32 v127, v111
	v_mov_b32_e32 v128, v112
	v_mov_b32_e32 v129, v113
	v_permlane16_swap_b32_e32 v98, v114
	v_permlane16_swap_b32_e32 v99, v115
	v_permlane16_swap_b32_e32 v100, v116
	v_permlane16_swap_b32_e32 v101, v117
	v_permlane16_swap_b32_e32 v102, v118
	v_permlane16_swap_b32_e32 v103, v119
	v_permlane16_swap_b32_e32 v104, v120
	v_permlane16_swap_b32_e32 v105, v121
	v_permlane16_swap_b32_e32 v106, v122
	v_permlane16_swap_b32_e32 v107, v123
	v_permlane16_swap_b32_e32 v108, v124
	v_permlane16_swap_b32_e32 v109, v125
	v_permlane16_swap_b32_e32 v110, v126
	v_permlane16_swap_b32_e32 v111, v127
	v_permlane16_swap_b32_e32 v112, v128
	v_permlane16_swap_b32_e32 v113, v129
	v_add_f32_e32 v98, v98, v114
	v_add_f32_e32 v99, v99, v115
	v_add_f32_e32 v100, v100, v116
	v_add_f32_e32 v101, v101, v117
	v_add_f32_e32 v102, v102, v118
	v_add_f32_e32 v103, v103, v119
	v_add_f32_e32 v104, v104, v120
	v_add_f32_e32 v105, v105, v121
	v_add_f32_e32 v106, v106, v122
	v_add_f32_e32 v107, v107, v123
	v_add_f32_e32 v108, v108, v124
	v_add_f32_e32 v109, v109, v125
	v_add_f32_e32 v110, v110, v126
	v_add_f32_e32 v111, v111, v127
	v_add_f32_e32 v112, v112, v128
	v_add_f32_e32 v113, v113, v129
	v_fmamk_f32 v98, v98, 0x3c000000, v1
	v_fmamk_f32 v99, v99, 0x3c000000, v1
	v_fmamk_f32 v100, v100, 0x3c000000, v1
	v_fmamk_f32 v101, v101, 0x3c000000, v1
	v_fmamk_f32 v102, v102, 0x3c000000, v1
	v_fmamk_f32 v103, v103, 0x3c000000, v1
	v_fmamk_f32 v104, v104, 0x3c000000, v1
	v_fmamk_f32 v105, v105, 0x3c000000, v1
	v_fmamk_f32 v106, v106, 0x3c000000, v1
	v_fmamk_f32 v107, v107, 0x3c000000, v1
	v_fmamk_f32 v108, v108, 0x3c000000, v1
	v_fmamk_f32 v109, v109, 0x3c000000, v1
	v_fmamk_f32 v110, v110, 0x3c000000, v1
	v_fmamk_f32 v111, v111, 0x3c000000, v1
	v_fmamk_f32 v112, v112, 0x3c000000, v1
	v_fmamk_f32 v113, v113, 0x3c000000, v1
	v_rsq_f32_e32 v98, v98
	v_rsq_f32_e32 v99, v99
	v_rsq_f32_e32 v100, v100
	v_rsq_f32_e32 v101, v101
	v_rsq_f32_e32 v102, v102
	v_rsq_f32_e32 v103, v103
	v_rsq_f32_e32 v104, v104
	v_rsq_f32_e32 v105, v105
	v_rsq_f32_e32 v106, v106
	v_rsq_f32_e32 v107, v107
	v_rsq_f32_e32 v108, v108
	v_rsq_f32_e32 v109, v109
	v_rsq_f32_e32 v110, v110
	v_rsq_f32_e32 v111, v111
	v_rsq_f32_e32 v112, v112
	v_rsq_f32_e32 v113, v113
	v_mul_f32_e32 v2, v2, v98
	v_mul_f32_e32 v18, v18, v98
	v_mul_f32_e32 v34, v34, v98
	v_mul_f32_e32 v50, v50, v98
	v_mul_f32_e32 v3, v3, v99
	v_mul_f32_e32 v19, v19, v99
	v_mul_f32_e32 v35, v35, v99
	v_mul_f32_e32 v51, v51, v99
	v_mul_f32_e32 v4, v4, v100
	v_mul_f32_e32 v20, v20, v100
	v_mul_f32_e32 v36, v36, v100
	v_mul_f32_e32 v52, v52, v100
	v_mul_f32_e32 v5, v5, v101
	v_mul_f32_e32 v21, v21, v101
	v_mul_f32_e32 v37, v37, v101
	v_mul_f32_e32 v53, v53, v101
	v_mul_f32_e32 v6, v6, v102
	v_mul_f32_e32 v22, v22, v102
	v_mul_f32_e32 v38, v38, v102
	v_mul_f32_e32 v54, v54, v102
	v_mul_f32_e32 v7, v7, v103
	v_mul_f32_e32 v23, v23, v103
	v_mul_f32_e32 v39, v39, v103
	v_mul_f32_e32 v55, v55, v103
	v_mul_f32_e32 v8, v8, v104
	v_mul_f32_e32 v24, v24, v104
	v_mul_f32_e32 v40, v40, v104
	v_mul_f32_e32 v56, v56, v104
	v_mul_f32_e32 v9, v9, v105
	v_mul_f32_e32 v25, v25, v105
	v_mul_f32_e32 v41, v41, v105
	v_mul_f32_e32 v57, v57, v105
	v_mul_f32_e32 v10, v10, v106
	v_mul_f32_e32 v26, v26, v106
	v_mul_f32_e32 v42, v42, v106
	v_mul_f32_e32 v58, v58, v106
	v_mul_f32_e32 v11, v11, v107
	v_mul_f32_e32 v27, v27, v107
	v_mul_f32_e32 v43, v43, v107
	v_mul_f32_e32 v59, v59, v107
	v_mul_f32_e32 v12, v12, v108
	v_mul_f32_e32 v28, v28, v108
	v_mul_f32_e32 v44, v44, v108
	v_mul_f32_e32 v60, v60, v108
	v_mul_f32_e32 v13, v13, v109
	v_mul_f32_e32 v29, v29, v109
	v_mul_f32_e32 v45, v45, v109
	v_mul_f32_e32 v61, v61, v109
	v_mul_f32_e32 v14, v14, v110
	v_mul_f32_e32 v30, v30, v110
	v_mul_f32_e32 v46, v46, v110
	v_mul_f32_e32 v62, v62, v110
	v_mul_f32_e32 v15, v15, v111
	v_mul_f32_e32 v31, v31, v111
	v_mul_f32_e32 v47, v47, v111
	v_mul_f32_e32 v63, v63, v111
	v_mul_f32_e32 v16, v16, v112
	v_mul_f32_e32 v32, v32, v112
	v_mul_f32_e32 v48, v48, v112
	v_mul_f32_e32 v64, v64, v112
	v_mul_f32_e32 v17, v17, v113
	v_mul_f32_e32 v33, v33, v113
	v_mul_f32_e32 v49, v49, v113
	v_mul_f32_e32 v65, v65, v113
	s_waitcnt vmcnt(0)
	ds_write_b128 v133, v[66:69]
	ds_write_b128 v133, v[70:73] offset:1024
	ds_write_b128 v133, v[74:77] offset:2048
	ds_write_b128 v133, v[78:81] offset:3072
	ds_write_b128 v133, v[82:85] offset:4096
	ds_write_b128 v133, v[86:89] offset:5120
	ds_write_b128 v133, v[90:93] offset:6144
	ds_write_b128 v133, v[94:97] offset:7168
	s_waitcnt lgkmcnt(0)
	v_mov_b32_e32 v114, 0xbfb8aa3b
	v_mov_b32_e32 v115, 0xbfb8aa3b
	v_mov_b32_e32 v116, 1.0
	v_mov_b32_e32 v117, 1.0
	ds_read_u16 v66, v132 offset:0
	ds_read_u16 v67, v132 offset:256
	ds_read_u16 v68, v132 offset:512
	ds_read_u16 v69, v132 offset:768
	ds_read_u16 v70, v132 offset:64
	ds_read_u16 v71, v132 offset:320
	ds_read_u16 v72, v132 offset:576
	ds_read_u16 v73, v132 offset:832
	ds_read_u16 v74, v132 offset:128
	ds_read_u16 v75, v132 offset:384
	ds_read_u16 v76, v132 offset:640
	ds_read_u16 v77, v132 offset:896
	ds_read_u16 v78, v132 offset:192
	ds_read_u16 v79, v132 offset:448
	ds_read_u16 v80, v132 offset:704
	ds_read_u16 v81, v132 offset:960
	s_waitcnt lgkmcnt(0)
; __device__ __forceinline__ int crow(int r, int hi) { return (r & 3) + 8 * (r >> 2) + 4 * hi; }
; __device__ __forceinline__ float bf2f(unsigned short b) { return __uint_as_float(((unsigned)b) << 16); }
; __device__ __forceinline__ unsigned short f2bf(float f) { return (unsigned short)(cvtpk(f, 0.f) & 0xffffu); }
; __device__ __forceinline__ void ret_output_unit(const bf16* __restrict__ Rb, const bf16* __restrict__ Sf, const bf16* __restrict__ Sb, bf16* Y, long rowbase, int h, float lgf, float lgb, char* lds) {
;     ...
;   const bf16* Gp = Rb + (rowbase + wid * QBLK) * 2048 + 1536 + h * 128; bf16* Yp = Y + (rowbase + wid * QBLK) * 512 + h * 128;
;   unsigned short gq[16][4];
; #pragma unroll
;   for (int r = 0; r < 16; ++r)
; #pragma unroll
;     for (int eb = 0; eb < 4; ++eb) gq[r][eb] = Gp[(long)crow(r, hi) * 2048 + 32 * eb + r32];
; #pragma unroll
;   for (int r = 0; r < 16; ++r) {
;     float ss = o[0][r] * o[0][r] + o[1][r] * o[1][r] + o[2][r] * o[2][r] + o[3][r] * o[3][r];
;     ss = half32_sum(ss);
;     const float rs = __builtin_amdgcn_rsqf(ss * (1.0f / 128.0f) + 1e-6f); const int row = crow(r, hi);
; #pragma unroll
;     for (int eb = 0; eb < 4; ++eb) { const float g = bf2f(gq[r][eb]);
;       const float sg = g * __builtin_amdgcn_rcpf(1.0f + __builtin_amdgcn_exp2f(-1.4426950408889634f * g));
;       Yp[(long)row * 512 + 32 * eb + r32] = f2bf(o[eb][r] * rs * sg); } }
	v_lshlrev_b32_e32 v66, 16, v66
	v_lshlrev_b32_e32 v67, 16, v67
	v_lshlrev_b32_e32 v68, 16, v68
	v_lshlrev_b32_e32 v69, 16, v69
	v_lshlrev_b32_e32 v70, 16, v70
	v_lshlrev_b32_e32 v71, 16, v71
	v_lshlrev_b32_e32 v72, 16, v72
	v_lshlrev_b32_e32 v73, 16, v73
	v_lshlrev_b32_e32 v74, 16, v74
	v_lshlrev_b32_e32 v75, 16, v75
	v_lshlrev_b32_e32 v76, 16, v76
	v_lshlrev_b32_e32 v77, 16, v77
	v_lshlrev_b32_e32 v78, 16, v78
	v_lshlrev_b32_e32 v79, 16, v79
	v_lshlrev_b32_e32 v80, 16, v80
	v_lshlrev_b32_e32 v81, 16, v81
	v_pk_mul_f32 v[82:83], v[66:67], v[114:115]
	v_pk_mul_f32 v[84:85], v[68:69], v[114:115]
	v_pk_mul_f32 v[86:87], v[70:71], v[114:115]
	v_pk_mul_f32 v[88:89], v[72:73], v[114:115]
	v_pk_mul_f32 v[90:91], v[74:75], v[114:115]
	v_pk_mul_f32 v[92:93], v[76:77], v[114:115]
	v_pk_mul_f32 v[94:95], v[78:79], v[114:115]
	v_pk_mul_f32 v[96:97], v[80:81], v[114:115]
	v_exp_f32_e32 v82, v82
	v_exp_f32_e32 v83, v83
	v_exp_f32_e32 v84, v84
	v_exp_f32_e32 v85, v85
	v_exp_f32_e32 v86, v86
	v_exp_f32_e32 v87, v87
	v_exp_f32_e32 v88, v88
	v_exp_f32_e32 v89, v89
	v_exp_f32_e32 v90, v90
	v_exp_f32_e32 v91, v91
	v_exp_f32_e32 v92, v92
	v_exp_f32_e32 v93, v93
	v_exp_f32_e32 v94, v94
	v_exp_f32_e32 v95, v95
	v_exp_f32_e32 v96, v96
	v_exp_f32_e32 v97, v97
	v_pk_add_f32 v[82:83], v[82:83], v[116:117]
	v_pk_add_f32 v[84:85], v[84:85], v[116:117]
	v_pk_add_f32 v[86:87], v[86:87], v[116:117]
	v_pk_add_f32 v[88:89], v[88:89], v[116:117]
	v_pk_add_f32 v[90:91], v[90:91], v[116:117]
	v_pk_add_f32 v[92:93], v[92:93], v[116:117]
	v_pk_add_f32 v[94:95], v[94:95], v[116:117]
	v_pk_add_f32 v[96:97], v[96:97], v[116:117]
	v_rcp_f32_e32 v82, v82
	v_rcp_f32_e32 v83, v83
	v_rcp_f32_e32 v84, v84
	v_rcp_f32_e32 v85, v85
	v_rcp_f32_e32 v86, v86
	v_rcp_f32_e32 v87, v87
	v_rcp_f32_e32 v88, v88
	v_rcp_f32_e32 v89, v89
	v_rcp_f32_e32 v90, v90
	v_rcp_f32_e32 v91, v91
	v_rcp_f32_e32 v92, v92
	v_rcp_f32_e32 v93, v93
	v_rcp_f32_e32 v94, v94
	v_rcp_f32_e32 v95, v95
	v_rcp_f32_e32 v96, v96
	v_rcp_f32_e32 v97, v97
	v_pk_mul_f32 v[66:67], v[82:83], v[66:67]
	v_pk_mul_f32 v[68:69], v[84:85], v[68:69]
	v_pk_mul_f32 v[70:71], v[86:87], v[70:71]
	v_pk_mul_f32 v[72:73], v[88:89], v[72:73]
	v_pk_mul_f32 v[74:75], v[90:91], v[74:75]
	v_pk_mul_f32 v[76:77], v[92:93], v[76:77]
	v_pk_mul_f32 v[78:79], v[94:95], v[78:79]
	v_pk_mul_f32 v[80:81], v[96:97], v[80:81]
	v_pk_mul_f32 v[66:67], v[66:67], v[50:51]
	v_pk_mul_f32 v[68:69], v[68:69], v[52:53]
	v_pk_mul_f32 v[70:71], v[70:71], v[34:35]
	v_pk_mul_f32 v[72:73], v[72:73], v[36:37]
	v_pk_mul_f32 v[74:75], v[74:75], v[18:19]
	v_pk_mul_f32 v[76:77], v[76:77], v[20:21]
	v_pk_mul_f32 v[78:79], v[78:79], v[2:3]
	v_pk_mul_f32 v[80:81], v[80:81], v[4:5]
	v_cvt_pk_bf16_f32 v82, v66, v70
	v_cvt_pk_bf16_f32 v83, v74, v78
	ds_write_b16 v132, v82 offset:0
	ds_write_b16_d16_hi v132, v82 offset:64
	ds_write_b16 v132, v83 offset:128
	ds_write_b16_d16_hi v132, v83 offset:192
	v_cvt_pk_bf16_f32 v84, v67, v71
	v_cvt_pk_bf16_f32 v85, v75, v79
	ds_write_b16 v132, v84 offset:256
	ds_write_b16_d16_hi v132, v84 offset:320
	ds_write_b16 v132, v85 offset:384
	ds_write_b16_d16_hi v132, v85 offset:448
	v_cvt_pk_bf16_f32 v86, v68, v72
	v_cvt_pk_bf16_f32 v87, v76, v80
	ds_write_b16 v132, v86 offset:512
	ds_write_b16_d16_hi v132, v86 offset:576
	ds_write_b16 v132, v87 offset:640
	ds_write_b16_d16_hi v132, v87 offset:704
	v_cvt_pk_bf16_f32 v88, v69, v73
	v_cvt_pk_bf16_f32 v89, v77, v81
	ds_write_b16 v132, v88 offset:768
	ds_write_b16_d16_hi v132, v88 offset:832
	ds_write_b16 v132, v89 offset:896
	ds_write_b16_d16_hi v132, v89 offset:960
	ds_read_u16 v66, v132 offset:2048
	ds_read_u16 v67, v132 offset:2304
	ds_read_u16 v68, v132 offset:2560
	ds_read_u16 v69, v132 offset:2816
	ds_read_u16 v70, v132 offset:2112
	ds_read_u16 v71, v132 offset:2368
	ds_read_u16 v72, v132 offset:2624
	ds_read_u16 v73, v132 offset:2880
	ds_read_u16 v74, v132 offset:2176
	ds_read_u16 v75, v132 offset:2432
	ds_read_u16 v76, v132 offset:2688
	ds_read_u16 v77, v132 offset:2944
	ds_read_u16 v78, v132 offset:2240
	ds_read_u16 v79, v132 offset:2496
	ds_read_u16 v80, v132 offset:2752
	ds_read_u16 v81, v132 offset:3008
	s_waitcnt lgkmcnt(0)
	v_lshlrev_b32_e32 v66, 16, v66
	v_lshlrev_b32_e32 v67, 16, v67
	v_lshlrev_b32_e32 v68, 16, v68
	v_lshlrev_b32_e32 v69, 16, v69
	v_lshlrev_b32_e32 v70, 16, v70
	v_lshlrev_b32_e32 v71, 16, v71
	v_lshlrev_b32_e32 v72, 16, v72
	v_lshlrev_b32_e32 v73, 16, v73
	v_lshlrev_b32_e32 v74, 16, v74
	v_lshlrev_b32_e32 v75, 16, v75
	v_lshlrev_b32_e32 v76, 16, v76
	v_lshlrev_b32_e32 v77, 16, v77
	v_lshlrev_b32_e32 v78, 16, v78
	v_lshlrev_b32_e32 v79, 16, v79
	v_lshlrev_b32_e32 v80, 16, v80
	v_lshlrev_b32_e32 v81, 16, v81
	v_pk_mul_f32 v[82:83], v[66:67], v[114:115]
	v_pk_mul_f32 v[84:85], v[68:69], v[114:115]
	v_pk_mul_f32 v[86:87], v[70:71], v[114:115]
	v_pk_mul_f32 v[88:89], v[72:73], v[114:115]
	v_pk_mul_f32 v[90:91], v[74:75], v[114:115]
	v_pk_mul_f32 v[92:93], v[76:77], v[114:115]
	v_pk_mul_f32 v[94:95], v[78:79], v[114:115]
	v_pk_mul_f32 v[96:97], v[80:81], v[114:115]
	v_exp_f32_e32 v82, v82
	v_exp_f32_e32 v83, v83
	v_exp_f32_e32 v84, v84
	v_exp_f32_e32 v85, v85
	v_exp_f32_e32 v86, v86
	v_exp_f32_e32 v87, v87
	v_exp_f32_e32 v88, v88
	v_exp_f32_e32 v89, v89
	v_exp_f32_e32 v90, v90
	v_exp_f32_e32 v91, v91
	v_exp_f32_e32 v92, v92
	v_exp_f32_e32 v93, v93
	v_exp_f32_e32 v94, v94
	v_exp_f32_e32 v95, v95
	v_exp_f32_e32 v96, v96
	v_exp_f32_e32 v97, v97
	v_pk_add_f32 v[82:83], v[82:83], v[116:117]
	v_pk_add_f32 v[84:85], v[84:85], v[116:117]
	v_pk_add_f32 v[86:87], v[86:87], v[116:117]
	v_pk_add_f32 v[88:89], v[88:89], v[116:117]
	v_pk_add_f32 v[90:91], v[90:91], v[116:117]
; __device__ __forceinline__ int crow(int r, int hi) { return (r & 3) + 8 * (r >> 2) + 4 * hi; }
; __device__ __forceinline__ float bf2f(unsigned short b) { return __uint_as_float(((unsigned)b) << 16); }
; __device__ __forceinline__ unsigned short f2bf(float f) { return (unsigned short)(cvtpk(f, 0.f) & 0xffffu); }
; __device__ __forceinline__ void ret_output_unit(const bf16* __restrict__ Rb, const bf16* __restrict__ Sf, const bf16* __restrict__ Sb, bf16* Y, long rowbase, int h, float lgf, float lgb, char* lds) {
;     ...
;   const bf16* Gp = Rb + (rowbase + wid * QBLK) * 2048 + 1536 + h * 128; bf16* Yp = Y + (rowbase + wid * QBLK) * 512 + h * 128;
;   unsigned short gq[16][4];
; #pragma unroll
;   for (int r = 0; r < 16; ++r)
; #pragma unroll
;     for (int eb = 0; eb < 4; ++eb) gq[r][eb] = Gp[(long)crow(r, hi) * 2048 + 32 * eb + r32];
; #pragma unroll
;   for (int r = 0; r < 16; ++r) {
;     float ss = o[0][r] * o[0][r] + o[1][r] * o[1][r] + o[2][r] * o[2][r] + o[3][r] * o[3][r];
;     ss = half32_sum(ss);
;     const float rs = __builtin_amdgcn_rsqf(ss * (1.0f / 128.0f) + 1e-6f); const int row = crow(r, hi);
; #pragma unroll
;     for (int eb = 0; eb < 4; ++eb) { const float g = bf2f(gq[r][eb]);
;       const float sg = g * __builtin_amdgcn_rcpf(1.0f + __builtin_amdgcn_exp2f(-1.4426950408889634f * g));
;       Yp[(long)row * 512 + 32 * eb + r32] = f2bf(o[eb][r] * rs * sg); } }
	v_pk_add_f32 v[92:93], v[92:93], v[116:117]
	v_pk_add_f32 v[94:95], v[94:95], v[116:117]
	v_pk_add_f32 v[96:97], v[96:97], v[116:117]
	v_rcp_f32_e32 v82, v82
	v_rcp_f32_e32 v83, v83
	v_rcp_f32_e32 v84, v84
	v_rcp_f32_e32 v85, v85
	v_rcp_f32_e32 v86, v86
	v_rcp_f32_e32 v87, v87
	v_rcp_f32_e32 v88, v88
	v_rcp_f32_e32 v89, v89
	v_rcp_f32_e32 v90, v90
	v_rcp_f32_e32 v91, v91
	v_rcp_f32_e32 v92, v92
	v_rcp_f32_e32 v93, v93
	v_rcp_f32_e32 v94, v94
	v_rcp_f32_e32 v95, v95
	v_rcp_f32_e32 v96, v96
	v_rcp_f32_e32 v97, v97
	v_pk_mul_f32 v[66:67], v[82:83], v[66:67]
	v_pk_mul_f32 v[68:69], v[84:85], v[68:69]
	v_pk_mul_f32 v[70:71], v[86:87], v[70:71]
	v_pk_mul_f32 v[72:73], v[88:89], v[72:73]
	v_pk_mul_f32 v[74:75], v[90:91], v[74:75]
	v_pk_mul_f32 v[76:77], v[92:93], v[76:77]
	v_pk_mul_f32 v[78:79], v[94:95], v[78:79]
	v_pk_mul_f32 v[80:81], v[96:97], v[80:81]
	v_pk_mul_f32 v[66:67], v[66:67], v[54:55]
	v_pk_mul_f32 v[68:69], v[68:69], v[56:57]
	v_pk_mul_f32 v[70:71], v[70:71], v[38:39]
	v_pk_mul_f32 v[72:73], v[72:73], v[40:41]
	v_pk_mul_f32 v[74:75], v[74:75], v[22:23]
	v_pk_mul_f32 v[76:77], v[76:77], v[24:25]
	v_pk_mul_f32 v[78:79], v[78:79], v[6:7]
	v_pk_mul_f32 v[80:81], v[80:81], v[8:9]
	v_cvt_pk_bf16_f32 v82, v66, v70
	v_cvt_pk_bf16_f32 v83, v74, v78
	ds_write_b16 v132, v82 offset:2048
	ds_write_b16_d16_hi v132, v82 offset:2112
	ds_write_b16 v132, v83 offset:2176
	ds_write_b16_d16_hi v132, v83 offset:2240
	v_cvt_pk_bf16_f32 v84, v67, v71
	v_cvt_pk_bf16_f32 v85, v75, v79
	ds_write_b16 v132, v84 offset:2304
	ds_write_b16_d16_hi v132, v84 offset:2368
	ds_write_b16 v132, v85 offset:2432
	ds_write_b16_d16_hi v132, v85 offset:2496
	v_cvt_pk_bf16_f32 v86, v68, v72
	v_cvt_pk_bf16_f32 v87, v76, v80
	ds_write_b16 v132, v86 offset:2560
	ds_write_b16_d16_hi v132, v86 offset:2624
	ds_write_b16 v132, v87 offset:2688
	ds_write_b16_d16_hi v132, v87 offset:2752
	v_cvt_pk_bf16_f32 v88, v69, v73
	v_cvt_pk_bf16_f32 v89, v77, v81
	ds_write_b16 v132, v88 offset:2816
	ds_write_b16_d16_hi v132, v88 offset:2880
	ds_write_b16 v132, v89 offset:2944
	ds_write_b16_d16_hi v132, v89 offset:3008
	ds_read_u16 v66, v132 offset:4096
	ds_read_u16 v67, v132 offset:4352
	ds_read_u16 v68, v132 offset:4608
	ds_read_u16 v69, v132 offset:4864
	ds_read_u16 v70, v132 offset:4160
	ds_read_u16 v71, v132 offset:4416
	ds_read_u16 v72, v132 offset:4672
	ds_read_u16 v73, v132 offset:4928
	ds_read_u16 v74, v132 offset:4224
	ds_read_u16 v75, v132 offset:4480
	ds_read_u16 v76, v132 offset:4736
	ds_read_u16 v77, v132 offset:4992
	ds_read_u16 v78, v132 offset:4288
	ds_read_u16 v79, v132 offset:4544
	ds_read_u16 v80, v132 offset:4800
	ds_read_u16 v81, v132 offset:5056
	s_waitcnt lgkmcnt(0)
	v_lshlrev_b32_e32 v66, 16, v66
	v_lshlrev_b32_e32 v67, 16, v67
	v_lshlrev_b32_e32 v68, 16, v68
	v_lshlrev_b32_e32 v69, 16, v69
	v_lshlrev_b32_e32 v70, 16, v70
	v_lshlrev_b32_e32 v71, 16, v71
	v_lshlrev_b32_e32 v72, 16, v72
	v_lshlrev_b32_e32 v73, 16, v73
	v_lshlrev_b32_e32 v74, 16, v74
	v_lshlrev_b32_e32 v75, 16, v75
	v_lshlrev_b32_e32 v76, 16, v76
	v_lshlrev_b32_e32 v77, 16, v77
	v_lshlrev_b32_e32 v78, 16, v78
	v_lshlrev_b32_e32 v79, 16, v79
	v_lshlrev_b32_e32 v80, 16, v80
	v_lshlrev_b32_e32 v81, 16, v81
	v_pk_mul_f32 v[82:83], v[66:67], v[114:115]
	v_pk_mul_f32 v[84:85], v[68:69], v[114:115]
	v_pk_mul_f32 v[86:87], v[70:71], v[114:115]
	v_pk_mul_f32 v[88:89], v[72:73], v[114:115]
	v_pk_mul_f32 v[90:91], v[74:75], v[114:115]
	v_pk_mul_f32 v[92:93], v[76:77], v[114:115]
	v_pk_mul_f32 v[94:95], v[78:79], v[114:115]
	v_pk_mul_f32 v[96:97], v[80:81], v[114:115]
	v_exp_f32_e32 v82, v82
	v_exp_f32_e32 v83, v83
	v_exp_f32_e32 v84, v84
	v_exp_f32_e32 v85, v85
	v_exp_f32_e32 v86, v86
	v_exp_f32_e32 v87, v87
	v_exp_f32_e32 v88, v88
	v_exp_f32_e32 v89, v89
	v_exp_f32_e32 v90, v90
	v_exp_f32_e32 v91, v91
	v_exp_f32_e32 v92, v92
	v_exp_f32_e32 v93, v93
	v_exp_f32_e32 v94, v94
	v_exp_f32_e32 v95, v95
	v_exp_f32_e32 v96, v96
	v_exp_f32_e32 v97, v97
	v_pk_add_f32 v[82:83], v[82:83], v[116:117]
	v_pk_add_f32 v[84:85], v[84:85], v[116:117]
	v_pk_add_f32 v[86:87], v[86:87], v[116:117]
	v_pk_add_f32 v[88:89], v[88:89], v[116:117]
	v_pk_add_f32 v[90:91], v[90:91], v[116:117]
	v_pk_add_f32 v[92:93], v[92:93], v[116:117]
	v_pk_add_f32 v[94:95], v[94:95], v[116:117]
	v_pk_add_f32 v[96:97], v[96:97], v[116:117]
	v_rcp_f32_e32 v82, v82
	v_rcp_f32_e32 v83, v83
	v_rcp_f32_e32 v84, v84
	v_rcp_f32_e32 v85, v85
	v_rcp_f32_e32 v86, v86
	v_rcp_f32_e32 v87, v87
	v_rcp_f32_e32 v88, v88
	v_rcp_f32_e32 v89, v89
	v_rcp_f32_e32 v90, v90
	v_rcp_f32_e32 v91, v91
	v_rcp_f32_e32 v92, v92
	v_rcp_f32_e32 v93, v93
	v_rcp_f32_e32 v94, v94
	v_rcp_f32_e32 v95, v95
	v_rcp_f32_e32 v96, v96
	v_rcp_f32_e32 v97, v97
	v_pk_mul_f32 v[66:67], v[82:83], v[66:67]
	v_pk_mul_f32 v[68:69], v[84:85], v[68:69]
	v_pk_mul_f32 v[70:71], v[86:87], v[70:71]
	v_pk_mul_f32 v[72:73], v[88:89], v[72:73]
	v_pk_mul_f32 v[74:75], v[90:91], v[74:75]
	v_pk_mul_f32 v[76:77], v[92:93], v[76:77]
	v_pk_mul_f32 v[78:79], v[94:95], v[78:79]
	v_pk_mul_f32 v[80:81], v[96:97], v[80:81]
	v_pk_mul_f32 v[66:67], v[66:67], v[58:59]
	v_pk_mul_f32 v[68:69], v[68:69], v[60:61]
	v_pk_mul_f32 v[70:71], v[70:71], v[42:43]
	v_pk_mul_f32 v[72:73], v[72:73], v[44:45]
	v_pk_mul_f32 v[74:75], v[74:75], v[26:27]
	v_pk_mul_f32 v[76:77], v[76:77], v[28:29]
	v_pk_mul_f32 v[78:79], v[78:79], v[10:11]
	v_pk_mul_f32 v[80:81], v[80:81], v[12:13]
	v_cvt_pk_bf16_f32 v82, v66, v70
	v_cvt_pk_bf16_f32 v83, v74, v78
	ds_write_b16 v132, v82 offset:4096
	ds_write_b16_d16_hi v132, v82 offset:4160
	ds_write_b16 v132, v83 offset:4224
	ds_write_b16_d16_hi v132, v83 offset:4288
	v_cvt_pk_bf16_f32 v84, v67, v71
	v_cvt_pk_bf16_f32 v85, v75, v79
	ds_write_b16 v132, v84 offset:4352
	ds_write_b16_d16_hi v132, v84 offset:4416
	ds_write_b16 v132, v85 offset:4480
	ds_write_b16_d16_hi v132, v85 offset:4544
	v_cvt_pk_bf16_f32 v86, v68, v72
	v_cvt_pk_bf16_f32 v87, v76, v80
	ds_write_b16 v132, v86 offset:4608
	ds_write_b16_d16_hi v132, v86 offset:4672
	ds_write_b16 v132, v87 offset:4736
	ds_write_b16_d16_hi v132, v87 offset:4800
	v_cvt_pk_bf16_f32 v88, v69, v73
	v_cvt_pk_bf16_f32 v89, v77, v81
	ds_write_b16 v132, v88 offset:4864
	ds_write_b16_d16_hi v132, v88 offset:4928
	ds_write_b16 v132, v89 offset:4992
	ds_write_b16_d16_hi v132, v89 offset:5056
	ds_read_u16 v66, v132 offset:6144
	ds_read_u16 v67, v132 offset:6400
	ds_read_u16 v68, v132 offset:6656
	ds_read_u16 v69, v132 offset:6912
	ds_read_u16 v70, v132 offset:6208
	ds_read_u16 v71, v132 offset:6464
	ds_read_u16 v72, v132 offset:6720
	ds_read_u16 v73, v132 offset:6976
	ds_read_u16 v74, v132 offset:6272
	ds_read_u16 v75, v132 offset:6528
	ds_read_u16 v76, v132 offset:6784
	ds_read_u16 v77, v132 offset:7040
	ds_read_u16 v78, v132 offset:6336
	ds_read_u16 v79, v132 offset:6592
	ds_read_u16 v80, v132 offset:6848
	ds_read_u16 v81, v132 offset:7104
	s_waitcnt lgkmcnt(0)
; __device__ __forceinline__ int crow(int r, int hi) { return (r & 3) + 8 * (r >> 2) + 4 * hi; }
; __device__ __forceinline__ float bf2f(unsigned short b) { return __uint_as_float(((unsigned)b) << 16); }
; __device__ __forceinline__ unsigned short f2bf(float f) { return (unsigned short)(cvtpk(f, 0.f) & 0xffffu); }
; __device__ __forceinline__ void ret_output_unit(const bf16* __restrict__ Rb, const bf16* __restrict__ Sf, const bf16* __restrict__ Sb, bf16* Y, long rowbase, int h, float lgf, float lgb, char* lds) {
;     ...
;   for (int r = 0; r < 16; ++r) {
;     float ss = o[0][r] * o[0][r] + o[1][r] * o[1][r] + o[2][r] * o[2][r] + o[3][r] * o[3][r];
;     ss = half32_sum(ss);
;     const float rs = __builtin_amdgcn_rsqf(ss * (1.0f / 128.0f) + 1e-6f); const int row = crow(r, hi);
; #pragma unroll
;     for (int eb = 0; eb < 4; ++eb) { const float g = bf2f(gq[r][eb]);
;       const float sg = g * __builtin_amdgcn_rcpf(1.0f + __builtin_amdgcn_exp2f(-1.4426950408889634f * g));
;       Yp[(long)row * 512 + 32 * eb + r32] = f2bf(o[eb][r] * rs * sg); } }
; __global__ void __launch_bounds__(NTHR, 2) mk_fwd(Args args) {
;     ...
;             for (int rep_ = 0; rep_ < NREP(11); ++rep_) for (int n = (P.vcu + (P.G >> 1)) % P.G; n < nrt; n += P.G) {
;                 int bh, blk; if (n < 512) { bh = n >> 3; blk = (n & 7) + 1; } else { bh = n - 512; blk = 0; }
;                 const int b = bh >> 2, h = bh & 3;
;                 const float lgf = -expf(IN(14)[l * 8 + h]) * 1.4426950408889634f, lgb = -expf(IN(14)[l * 8 + 4 + h]) * 1.4426950408889634f;
;                 const long rowbase = blk ? (long)b * SEQ + (blk - 1) * 256 : (long)TLAT + b * CTXL;
;                 const bf16* sf = blk ? P_STS + ((size_t)(bh * 8 + blk - 1) * 2) * 16384 : nullptr;
;                 att::ret_output_unit(P_RB, sf, blk ? sf + 16384 : nullptr, P_YR, rowbase, h, lgf, lgb, (char*)lds);
;                 __syncthreads(); } } }
	v_lshlrev_b32_e32 v66, 16, v66
	v_lshlrev_b32_e32 v67, 16, v67
	v_lshlrev_b32_e32 v68, 16, v68
	v_lshlrev_b32_e32 v69, 16, v69
	v_lshlrev_b32_e32 v70, 16, v70
	v_lshlrev_b32_e32 v71, 16, v71
	v_lshlrev_b32_e32 v72, 16, v72
	v_lshlrev_b32_e32 v73, 16, v73
	v_lshlrev_b32_e32 v74, 16, v74
	v_lshlrev_b32_e32 v75, 16, v75
	v_lshlrev_b32_e32 v76, 16, v76
	v_lshlrev_b32_e32 v77, 16, v77
	v_lshlrev_b32_e32 v78, 16, v78
	v_lshlrev_b32_e32 v79, 16, v79
	v_lshlrev_b32_e32 v80, 16, v80
	v_lshlrev_b32_e32 v81, 16, v81
	v_pk_mul_f32 v[82:83], v[66:67], v[114:115]
	v_pk_mul_f32 v[84:85], v[68:69], v[114:115]
	v_pk_mul_f32 v[86:87], v[70:71], v[114:115]
	v_pk_mul_f32 v[88:89], v[72:73], v[114:115]
	v_pk_mul_f32 v[90:91], v[74:75], v[114:115]
	v_pk_mul_f32 v[92:93], v[76:77], v[114:115]
	v_pk_mul_f32 v[94:95], v[78:79], v[114:115]
	v_pk_mul_f32 v[96:97], v[80:81], v[114:115]
	v_exp_f32_e32 v82, v82
	v_exp_f32_e32 v83, v83
	v_exp_f32_e32 v84, v84
	v_exp_f32_e32 v85, v85
	v_exp_f32_e32 v86, v86
	v_exp_f32_e32 v87, v87
	v_exp_f32_e32 v88, v88
	v_exp_f32_e32 v89, v89
	v_exp_f32_e32 v90, v90
	v_exp_f32_e32 v91, v91
	v_exp_f32_e32 v92, v92
	v_exp_f32_e32 v93, v93
	v_exp_f32_e32 v94, v94
	v_exp_f32_e32 v95, v95
	v_exp_f32_e32 v96, v96
	v_exp_f32_e32 v97, v97
	v_pk_add_f32 v[82:83], v[82:83], v[116:117]
	v_pk_add_f32 v[84:85], v[84:85], v[116:117]
	v_pk_add_f32 v[86:87], v[86:87], v[116:117]
	v_pk_add_f32 v[88:89], v[88:89], v[116:117]
	v_pk_add_f32 v[90:91], v[90:91], v[116:117]
	v_pk_add_f32 v[92:93], v[92:93], v[116:117]
	v_pk_add_f32 v[94:95], v[94:95], v[116:117]
	v_pk_add_f32 v[96:97], v[96:97], v[116:117]
	v_rcp_f32_e32 v82, v82
	v_rcp_f32_e32 v83, v83
	v_rcp_f32_e32 v84, v84
	v_rcp_f32_e32 v85, v85
	v_rcp_f32_e32 v86, v86
	v_rcp_f32_e32 v87, v87
	v_rcp_f32_e32 v88, v88
	v_rcp_f32_e32 v89, v89
	v_rcp_f32_e32 v90, v90
	v_rcp_f32_e32 v91, v91
	v_rcp_f32_e32 v92, v92
	v_rcp_f32_e32 v93, v93
	v_rcp_f32_e32 v94, v94
	v_rcp_f32_e32 v95, v95
	v_rcp_f32_e32 v96, v96
	v_rcp_f32_e32 v97, v97
	v_pk_mul_f32 v[66:67], v[82:83], v[66:67]
	v_pk_mul_f32 v[68:69], v[84:85], v[68:69]
	v_pk_mul_f32 v[70:71], v[86:87], v[70:71]
	v_pk_mul_f32 v[72:73], v[88:89], v[72:73]
	v_pk_mul_f32 v[74:75], v[90:91], v[74:75]
	v_pk_mul_f32 v[76:77], v[92:93], v[76:77]
	v_pk_mul_f32 v[78:79], v[94:95], v[78:79]
	v_pk_mul_f32 v[80:81], v[96:97], v[80:81]
	v_pk_mul_f32 v[66:67], v[66:67], v[62:63]
	v_pk_mul_f32 v[68:69], v[68:69], v[64:65]
	v_pk_mul_f32 v[70:71], v[70:71], v[46:47]
	v_pk_mul_f32 v[72:73], v[72:73], v[48:49]
	v_pk_mul_f32 v[74:75], v[74:75], v[30:31]
	v_pk_mul_f32 v[76:77], v[76:77], v[32:33]
	v_pk_mul_f32 v[78:79], v[78:79], v[14:15]
	v_pk_mul_f32 v[80:81], v[80:81], v[16:17]
	v_cvt_pk_bf16_f32 v82, v66, v70
	v_cvt_pk_bf16_f32 v83, v74, v78
	ds_write_b16 v132, v82 offset:6144
	ds_write_b16_d16_hi v132, v82 offset:6208
	ds_write_b16 v132, v83 offset:6272
	ds_write_b16_d16_hi v132, v83 offset:6336
	v_cvt_pk_bf16_f32 v84, v67, v71
	v_cvt_pk_bf16_f32 v85, v75, v79
	ds_write_b16 v132, v84 offset:6400
	ds_write_b16_d16_hi v132, v84 offset:6464
	ds_write_b16 v132, v85 offset:6528
	ds_write_b16_d16_hi v132, v85 offset:6592
	v_cvt_pk_bf16_f32 v86, v68, v72
	v_cvt_pk_bf16_f32 v87, v76, v80
	ds_write_b16 v132, v86 offset:6656
	ds_write_b16_d16_hi v132, v86 offset:6720
	ds_write_b16 v132, v87 offset:6784
	ds_write_b16_d16_hi v132, v87 offset:6848
	v_cvt_pk_bf16_f32 v88, v69, v73
	v_cvt_pk_bf16_f32 v89, v77, v81
	ds_write_b16 v132, v88 offset:6912
	ds_write_b16_d16_hi v132, v88 offset:6976
	ds_write_b16 v132, v89 offset:7040
	ds_write_b16_d16_hi v132, v89 offset:7104
	s_waitcnt lgkmcnt(0)
	ds_read_b128 v[2:5], v133
	ds_read_b128 v[6:9], v133 offset:1024
	ds_read_b128 v[10:13], v133 offset:2048
	ds_read_b128 v[14:17], v133 offset:3072
	ds_read_b128 v[18:21], v133 offset:4096
	ds_read_b128 v[22:25], v133 offset:5120
	ds_read_b128 v[26:29], v133 offset:6144
	ds_read_b128 v[30:33], v133 offset:7168
	s_waitcnt lgkmcnt(7)
	global_store_dwordx4 v186, v[2:5], s[34:35]
	s_nop 1
	v_add_u32_e32 v186, 0x1000, v186
	s_waitcnt lgkmcnt(6)
	global_store_dwordx4 v186, v[6:9], s[34:35]
	s_nop 1
	v_add_u32_e32 v186, 0x1000, v186
	s_waitcnt lgkmcnt(5)
	global_store_dwordx4 v186, v[10:13], s[34:35]
	s_nop 1
	v_add_u32_e32 v186, 0x1000, v186
	s_waitcnt lgkmcnt(4)
	global_store_dwordx4 v186, v[14:17], s[34:35]
	s_nop 1
	v_add_u32_e32 v186, 0x1000, v186
	s_waitcnt lgkmcnt(3)
	global_store_dwordx4 v186, v[18:21], s[34:35]
	s_nop 1
	v_add_u32_e32 v186, 0x1000, v186
	s_waitcnt lgkmcnt(2)
	global_store_dwordx4 v186, v[22:25], s[34:35]
	s_nop 1
	v_add_u32_e32 v186, 0x1000, v186
	s_waitcnt lgkmcnt(1)
	global_store_dwordx4 v186, v[26:29], s[34:35]
	s_nop 1
	v_add_u32_e32 v186, 0x1000, v186
	s_waitcnt lgkmcnt(0)
	global_store_dwordx4 v186, v[30:33], s[34:35]
	v_ashrrev_i32_e32 v147, 31, v146
	v_lshlrev_b32_e32 v186, 1, v151
	s_add_i32 s22, s22, s41
	s_cmp_lt_i32 s22, s83
	s_waitcnt vmcnt(63) expcnt(7) lgkmcnt(15)
	s_barrier
	s_cbranch_scc1 .LBB0_996
